# batched (parallel) global loads in staging loops: hy_lat filter taps, conv_hy tile staging, all prep_conv weight-tile staging copies; norm-phase wait relaxations
# speedup vs baseline: 1.0226x; 1.0226x over previous
; __device__ __forceinline__ void prep_conv_item(const Params& p, int l, int it, char* smem, int wvi) {
;     ...
;   const int ntile = it / KT, ktile = it - ntile * KT;
;   const int n0 = ntile * 64, k0 = ktile * 64;
;   float* sT = reinterpret_cast<float*>(smem);
;   __syncthreads();
; #pragma unroll 4
;   for (int i = 0; i < 16; ++i) {
;     const int idx = tid + 256 * i, k = idx >> 6, n = idx & 63;
;     const int sc = srccol(mode, n0 + n);
;     sT[k * 65 + n] = (sc >= 0) ? src[(size_t)(k0 + k) * ld + sc] : 0.f;
;   }
.LBB0_101:
	v_cvt_f32_ubyte0_e32 v0, s3
	v_rcp_iflag_f32_e32 v0, v0
	v_readlane_b32 s14, v245, 47
	s_add_u32 s8, s90, s8
	v_readlane_b32 s15, v245, 48
	v_mul_f32_e32 v0, 0x4f7ffffe, v0
	v_cvt_u32_f32_e32 v0, v0
	s_addc_u32 s9, s91, s15
	s_sub_i32 s15, 0, s3
	s_abs_i32 s14, s10
	v_readfirstlane_b32 s16, v0
	s_mul_i32 s15, s15, s16
	s_mul_hi_u32 s15, s16, s15
	s_add_i32 s16, s16, s15
	s_mul_hi_u32 s15, s14, s16
	s_mul_i32 s16, s15, s3
	s_sub_i32 s14, s14, s16
	s_ashr_i32 s11, s10, 31
	s_add_i32 s16, s15, 1
	s_sub_i32 s17, s14, s3
	s_cmp_ge_u32 s14, s3
	s_cselect_b32 s15, s16, s15
	s_cselect_b32 s14, s17, s14
	s_add_i32 s16, s15, 1
	s_cmp_ge_u32 s14, s3
	s_cselect_b32 s14, s16, s15
	s_xor_b32 s14, s14, s11
	s_sub_i32 s11, s14, s11
	s_mul_i32 s3, s11, s3
	v_bfe_i32 v1, v3, 4, 1
	s_lshl_b32 s14, s11, 5
	s_sub_i32 s10, s10, s3
	s_lshl_b32 s3, s11, 6
	v_and_b32_e32 v2, 63, v3
	v_and_b32_e32 v1, 0xb00, v1
	s_and_b32 s14, s14, 0xffffff80
	v_or_b32_e32 v0, s3, v2
	v_add_u32_e32 v1, s14, v1
	s_movk_i32 s14, 0x60
	s_lshl_b32 s11, s11, 1
	v_and_or_b32 v1, v0, s14, v1
	s_and_b32 s11, s11, 4
	s_waitcnt vmcnt(0)
	v_and_b32_e32 v5, 3, v3
	v_or3_b32 v1, v1, s11, v5
	v_lshrrev_b32_e32 v5, 2, v3
	s_load_dwordx2 s[8:9], s[8:9], 0x0
	v_and_b32_e32 v5, 4, v5
	s_movk_i32 s11, 0xffe3
	v_and_or_b32 v0, v0, s11, v5
	v_lshlrev_b32_e32 v4, 1, v3
	v_cndmask_b32_e64 v0, v1, v0, s[4:5]
	v_and_or_b32 v176, v4, 24, v0
	s_mov_b32 s7, 0
	s_lshl_b32 s10, s10, 6
	v_cmp_lt_i32_e32 vcc, -1, v0
	v_lshl_add_u64 v[0:1], v[176:177], 2, s[12:13]
	v_lshl_add_u32 v2, v2, 2, s52
	s_waitcnt lgkmcnt(0)
	s_barrier
	v_ashrrev_i32_e32 v30, 6, v3
	v_add_u32_e32 v31, s10, v30
	v_mad_i64_i32 v[26:27], s[12:13], s6, v31, 0
	v_lshl_add_u64 v[26:27], v[26:27], 2, v[0:1]
	v_mad_u64_u32 v[28:29], s[12:13], v30, s56, v[2:3]
	v_mov_b32_e32 v10, 0
	v_mov_b32_e32 v11, 0
	v_mov_b32_e32 v12, 0
	v_mov_b32_e32 v13, 0
	v_mov_b32_e32 v14, 0
	v_mov_b32_e32 v15, 0
	v_mov_b32_e32 v16, 0
	v_mov_b32_e32 v17, 0
	v_mov_b32_e32 v18, 0
	v_mov_b32_e32 v19, 0
	v_mov_b32_e32 v20, 0
	v_mov_b32_e32 v21, 0
	v_mov_b32_e32 v22, 0
	v_mov_b32_e32 v23, 0
	v_mov_b32_e32 v24, 0
	v_mov_b32_e32 v25, 0
	s_lshl_b32 s12, s6, 4
	s_mov_b32 s13, 0
	s_and_saveexec_b64 s[4:5], vcc
	global_load_dword v10, v[26:27], off
	v_lshl_add_u64 v[26:27], v[26:27], 0, s[12:13]
	global_load_dword v11, v[26:27], off
	v_lshl_add_u64 v[26:27], v[26:27], 0, s[12:13]
	global_load_dword v12, v[26:27], off
	v_lshl_add_u64 v[26:27], v[26:27], 0, s[12:13]
	global_load_dword v13, v[26:27], off
	v_lshl_add_u64 v[26:27], v[26:27], 0, s[12:13]
	global_load_dword v14, v[26:27], off
	v_lshl_add_u64 v[26:27], v[26:27], 0, s[12:13]
	global_load_dword v15, v[26:27], off
	v_lshl_add_u64 v[26:27], v[26:27], 0, s[12:13]
	global_load_dword v16, v[26:27], off
	v_lshl_add_u64 v[26:27], v[26:27], 0, s[12:13]
	global_load_dword v17, v[26:27], off
	v_lshl_add_u64 v[26:27], v[26:27], 0, s[12:13]
	global_load_dword v18, v[26:27], off
	v_lshl_add_u64 v[26:27], v[26:27], 0, s[12:13]
	global_load_dword v19, v[26:27], off
	v_lshl_add_u64 v[26:27], v[26:27], 0, s[12:13]
	global_load_dword v20, v[26:27], off
	v_lshl_add_u64 v[26:27], v[26:27], 0, s[12:13]
	global_load_dword v21, v[26:27], off
	v_lshl_add_u64 v[26:27], v[26:27], 0, s[12:13]
	global_load_dword v22, v[26:27], off
	v_lshl_add_u64 v[26:27], v[26:27], 0, s[12:13]
	global_load_dword v23, v[26:27], off
	v_lshl_add_u64 v[26:27], v[26:27], 0, s[12:13]
	global_load_dword v24, v[26:27], off
	v_lshl_add_u64 v[26:27], v[26:27], 0, s[12:13]
	global_load_dword v25, v[26:27], off
	s_or_b64 exec, exec, s[4:5]
	s_waitcnt vmcnt(15)
	ds_write_b32 v28, v10
	s_waitcnt vmcnt(14)
	ds_write_b32 v28, v11 offset:1040
	s_waitcnt vmcnt(13)
	ds_write_b32 v28, v12 offset:2080
	s_waitcnt vmcnt(12)
	ds_write_b32 v28, v13 offset:3120
	s_waitcnt vmcnt(11)
	ds_write_b32 v28, v14 offset:4160
	s_waitcnt vmcnt(10)
	ds_write_b32 v28, v15 offset:5200
	s_waitcnt vmcnt(9)
	ds_write_b32 v28, v16 offset:6240
	s_waitcnt vmcnt(8)
	ds_write_b32 v28, v17 offset:7280
	s_waitcnt vmcnt(7)
	ds_write_b32 v28, v18 offset:8320
	s_waitcnt vmcnt(6)
	ds_write_b32 v28, v19 offset:9360
	s_waitcnt vmcnt(5)
	ds_write_b32 v28, v20 offset:10400
	s_waitcnt vmcnt(4)
	ds_write_b32 v28, v21 offset:11440
	s_waitcnt vmcnt(3)
	ds_write_b32 v28, v22 offset:12480
	s_waitcnt vmcnt(2)
	ds_write_b32 v28, v23 offset:13520
	s_waitcnt vmcnt(1)
	ds_write_b32 v28, v24 offset:14560
	s_waitcnt vmcnt(0)
	ds_write_b32 v28, v25 offset:15600
	s_branch .LBB0_95

; __device__ __forceinline__ int otid(int wvi) { int t = (wvi & 3) * 64 + lane_id(); asm volatile("" : "+v"(t)); return t; }
; __device__ __forceinline__ int srccol(int mode, int n) {
;     ...
;     const int tile = n >> 8, r = n & 255, bj = r >> 7, wc = (r >> 5) & 3, q = (r >> 4) & 1, i = r & 15;
;     return (q ? DFF : 0) + tile * 128 + wc * 32 + (i >> 2) * 8 + bj * 4 + (i & 3);
;   }
;   const int L = (n & ~31) + perm32(n & 31);
;   if (L < 2304) return L;
;   if (L < 3072) return L + 16;
;   if (L < 3088) return L - 768;
;   return -1;
; }
; __device__ __forceinline__ void prep_conv_item(const Params& p, int l, int it, char* smem, int wvi) {
;   const int tid = otid(wvi);
;   const float* src; bf16_t* dst; int ld, K, mode, KT;
;   if (it < 2816) { const int i = it / 1408; it -= i * 1408; src = p.ffn_w_in + (size_t)(l * 2 + i) * DM * 2 * DFF; dst = i ? p.wFin1 : p.wFin0; ld = 2 * DFF; K = DM; mode = 1; KT = 16; }
;   else if (it < 4224) { it -= 2816; const int i = it / 704; it -= i * 704; src = p.ffn_w_out + (size_t)(l * 2 + i) * DFF * DM; dst = i ? p.wFout1 : p.wFout0; ld = DM; K = DFF; mode = 0; KT = 44; }
;   else if (it < 5056) { it -= 4224; src = p.w_in + (size_t)l * DM * DIN; dst = p.wIn; ld = DIN; K = DM; mode = 2; KT = 16; }
;   else { it -= 5056; src = p.w_out + (size_t)l * DM * DM; dst = p.wOut; ld = DM; K = DM; mode = 0; KT = 16; }
;   const int ntile = it / KT, ktile = it - ntile * KT;
;   const int n0 = ntile * 64, k0 = ktile * 64;
;   float* sT = reinterpret_cast<float*>(smem);
;   __syncthreads();
; #pragma unroll 4
;   for (int i = 0; i < 16; ++i) {
;     const int idx = tid + 256 * i, k = idx >> 6, n = idx & 63;
;     const int sc = srccol(mode, n0 + n);
;     sT[k * 65 + n] = (sc >= 0) ? src[(size_t)(k0 + k) * ld + sc] : 0.f;
;   }
.LBB0_184:
	s_mul_hi_i32 s2, s1, 0x2e8ba2e9
	s_lshr_b32 s3, s2, 31
	s_ashr_i32 s2, s2, 8
	s_add_i32 s2, s2, s3
	s_mul_i32 s3, s2, 0xfffffa80
	s_add_i32 s2, s2, s0
	v_readlane_b32 s8, v246, 6
	s_add_i32 s4, s3, s1
	s_mul_hi_i32 s3, s2, 0x1600000
	s_mul_i32 s2, s2, 0x1600000
	v_readlane_b32 s22, v246, 20
	v_readlane_b32 s23, v246, 21
	s_add_u32 s6, s22, s2
	s_addc_u32 s7, s23, s3
	s_cmpk_gt_i32 s1, 0xfa80
	s_movk_i32 s2, 0xf0
	s_cselect_b32 s2, s2, 0xf8
	s_add_u32 s2, s90, s2
	s_addc_u32 s3, s91, 0
	s_ashr_i32 s8, s4, 31
	s_lshr_b32 s8, s8, 28
	v_readlane_b32 s9, v246, 7
	s_add_i32 s8, s4, s8
	v_readlane_b32 s10, v246, 8
	s_ashr_i32 s9, s8, 4
	v_mbcnt_lo_u32_b32 v0, -1, 0
	v_mbcnt_hi_u32_b32 v0, -1, v0
	s_lshl_b32 s10, s9, 10
	v_add_u32_e32 v3, s95, v0
	s_lshl_b32 s4, s4, 6
	s_load_dwordx2 s[2:3], s[2:3], 0x0
	s_lshl_b32 s8, s9, 6
	s_sub_i32 s4, s4, s10
	v_bfe_i32 v1, v3, 4, 1
	s_lshl_b32 s10, s9, 5
	v_lshlrev_b32_e32 v4, 1, v3
	s_lshl_b32 s9, s9, 1
	v_and_b32_e32 v2, 63, v3
	v_and_b32_e32 v1, 0xb00, v1
	s_and_b32 s10, s10, 0xffffff80
	v_and_b32_e32 v4, 24, v4
	s_and_b32 s9, s9, 4
	v_and_b32_e32 v5, 3, v3
	v_bitop3_b32 v0, s8, v208, v2 bitop3:0xc8
	v_add_u32_e32 v1, s10, v1
	v_or3_b32 v4, v4, v5, s9
	v_or3_b32 v176, v4, v0, v1
	s_mov_b32 s5, 0
	v_cmp_lt_i32_e32 vcc, -1, v1
	v_lshl_add_u64 v[0:1], v[176:177], 2, s[6:7]
	v_lshl_add_u32 v2, v2, 2, s52
	v_readlane_b32 s11, v246, 9
	v_readlane_b32 s12, v246, 10
	v_readlane_b32 s13, v246, 11
	v_readlane_b32 s14, v246, 12
	v_readlane_b32 s15, v246, 13
	v_readlane_b32 s16, v246, 14
	v_readlane_b32 s17, v246, 15
	v_readlane_b32 s18, v246, 16
	v_readlane_b32 s19, v246, 17
	v_readlane_b32 s20, v246, 18
	v_readlane_b32 s21, v246, 19
	s_waitcnt lgkmcnt(0)
	s_barrier
	v_ashrrev_i32_e32 v30, 6, v3
	v_add_u32_e32 v31, s4, v30
	v_mad_i64_i32 v[26:27], s[10:11], v31, s66, v[0:1]
	v_mad_u64_u32 v[28:29], s[10:11], v30, s56, v[2:3]
	v_mov_b32_e32 v10, 0
	v_mov_b32_e32 v11, 0
	v_mov_b32_e32 v12, 0
	v_mov_b32_e32 v13, 0
	v_mov_b32_e32 v14, 0
	v_mov_b32_e32 v15, 0
	v_mov_b32_e32 v16, 0
	v_mov_b32_e32 v17, 0
	v_mov_b32_e32 v18, 0
	v_mov_b32_e32 v19, 0
	v_mov_b32_e32 v20, 0
	v_mov_b32_e32 v21, 0
	v_mov_b32_e32 v22, 0
	v_mov_b32_e32 v23, 0
	v_mov_b32_e32 v24, 0
	v_mov_b32_e32 v25, 0
	s_lshl_b32 s10, s66, 2
	s_mov_b32 s11, 0
	s_and_saveexec_b64 s[6:7], vcc
	global_load_dword v10, v[26:27], off
	v_lshl_add_u64 v[26:27], v[26:27], 0, s[10:11]
	global_load_dword v11, v[26:27], off
	v_lshl_add_u64 v[26:27], v[26:27], 0, s[10:11]
	global_load_dword v12, v[26:27], off
	v_lshl_add_u64 v[26:27], v[26:27], 0, s[10:11]
	global_load_dword v13, v[26:27], off
	v_lshl_add_u64 v[26:27], v[26:27], 0, s[10:11]
	global_load_dword v14, v[26:27], off
	v_lshl_add_u64 v[26:27], v[26:27], 0, s[10:11]
	global_load_dword v15, v[26:27], off
	v_lshl_add_u64 v[26:27], v[26:27], 0, s[10:11]
	global_load_dword v16, v[26:27], off
	v_lshl_add_u64 v[26:27], v[26:27], 0, s[10:11]
	global_load_dword v17, v[26:27], off
	v_lshl_add_u64 v[26:27], v[26:27], 0, s[10:11]
	global_load_dword v18, v[26:27], off
	v_lshl_add_u64 v[26:27], v[26:27], 0, s[10:11]
	global_load_dword v19, v[26:27], off
	v_lshl_add_u64 v[26:27], v[26:27], 0, s[10:11]
	global_load_dword v20, v[26:27], off
	v_lshl_add_u64 v[26:27], v[26:27], 0, s[10:11]
	global_load_dword v21, v[26:27], off
	v_lshl_add_u64 v[26:27], v[26:27], 0, s[10:11]
	global_load_dword v22, v[26:27], off
	v_lshl_add_u64 v[26:27], v[26:27], 0, s[10:11]
	global_load_dword v23, v[26:27], off
	v_lshl_add_u64 v[26:27], v[26:27], 0, s[10:11]
	global_load_dword v24, v[26:27], off
	v_lshl_add_u64 v[26:27], v[26:27], 0, s[10:11]
	global_load_dword v25, v[26:27], off
	s_or_b64 exec, exec, s[6:7]
	s_waitcnt vmcnt(15)
	ds_write_b32 v28, v10
	s_waitcnt vmcnt(14)
	ds_write_b32 v28, v11 offset:1040
	s_waitcnt vmcnt(13)
	ds_write_b32 v28, v12 offset:2080
	s_waitcnt vmcnt(12)
	ds_write_b32 v28, v13 offset:3120
	s_waitcnt vmcnt(11)
	ds_write_b32 v28, v14 offset:4160
	s_waitcnt vmcnt(10)
	ds_write_b32 v28, v15 offset:5200
	s_waitcnt vmcnt(9)
	ds_write_b32 v28, v16 offset:6240
	s_waitcnt vmcnt(8)
	ds_write_b32 v28, v17 offset:7280
	s_waitcnt vmcnt(7)
	ds_write_b32 v28, v18 offset:8320
	s_waitcnt vmcnt(6)
	ds_write_b32 v28, v19 offset:9360
	s_waitcnt vmcnt(5)
	ds_write_b32 v28, v20 offset:10400
	s_waitcnt vmcnt(4)
	ds_write_b32 v28, v21 offset:11440
	s_waitcnt vmcnt(3)
	ds_write_b32 v28, v22 offset:12480
	s_waitcnt vmcnt(2)
	ds_write_b32 v28, v23 offset:13520
	s_waitcnt vmcnt(1)
	ds_write_b32 v28, v24 offset:14560
	s_waitcnt vmcnt(0)
	ds_write_b32 v28, v25 offset:15600
	s_branch .LBB0_183

; __device__ __forceinline__ int otid(int wvi) { int t = (wvi & 3) * 64 + lane_id(); asm volatile("" : "+v"(t)); return t; }
; __device__ __forceinline__ int srccol(int mode, int n) {
;     ...
;     const int tile = n >> 8, r = n & 255, bj = r >> 7, wc = (r >> 5) & 3, q = (r >> 4) & 1, i = r & 15;
;     return (q ? DFF : 0) + tile * 128 + wc * 32 + (i >> 2) * 8 + bj * 4 + (i & 3);
;   }
;   const int L = (n & ~31) + perm32(n & 31);
;   if (L < 2304) return L;
;   if (L < 3072) return L + 16;
;   if (L < 3088) return L - 768;
;   return -1;
; }
; __device__ __forceinline__ void prep_conv_item(const Params& p, int l, int it, char* smem, int wvi) {
;   const int tid = otid(wvi);
;   const float* src; bf16_t* dst; int ld, K, mode, KT;
;   if (it < 2816) { const int i = it / 1408; it -= i * 1408; src = p.ffn_w_in + (size_t)(l * 2 + i) * DM * 2 * DFF; dst = i ? p.wFin1 : p.wFin0; ld = 2 * DFF; K = DM; mode = 1; KT = 16; }
;   else if (it < 4224) { it -= 2816; const int i = it / 704; it -= i * 704; src = p.ffn_w_out + (size_t)(l * 2 + i) * DFF * DM; dst = i ? p.wFout1 : p.wFout0; ld = DM; K = DFF; mode = 0; KT = 44; }
;   else if (it < 5056) { it -= 4224; src = p.w_in + (size_t)l * DM * DIN; dst = p.wIn; ld = DIN; K = DM; mode = 2; KT = 16; }
;   else { it -= 5056; src = p.w_out + (size_t)l * DM * DM; dst = p.wOut; ld = DM; K = DM; mode = 0; KT = 16; }
;   const int ntile = it / KT, ktile = it - ntile * KT;
;   const int n0 = ntile * 64, k0 = ktile * 64;
;   float* sT = reinterpret_cast<float*>(smem);
;   __syncthreads();
; #pragma unroll 4
;   for (int i = 0; i < 16; ++i) {
;     const int idx = tid + 256 * i, k = idx >> 6, n = idx & 63;
;     const int sc = srccol(mode, n0 + n);
;     sT[k * 65 + n] = (sc >= 0) ? src[(size_t)(k0 + k) * ld + sc] : 0.f;
;   }
.LBB0_198:
	s_add_i32 s2, s1, 0x580
	s_mul_hi_i32 s3, s2, 0x2e8ba2e9
	s_lshr_b32 s4, s3, 31
	s_ashr_i32 s3, s3, 8
	s_add_i32 s3, s3, s4
	s_mul_i32 s4, s3, 0xfffffa80
	s_add_i32 s4, s4, s2
	s_add_i32 s2, s3, s8
	v_readlane_b32 s12, v246, 6
	s_mul_hi_i32 s3, s2, 0x1600000
	s_mul_i32 s2, s2, 0x1600000
	v_readlane_b32 s26, v246, 20
	v_readlane_b32 s27, v246, 21
	s_add_u32 s6, s26, s2
	s_addc_u32 s7, s27, s3
	s_cmp_gt_u32 s1, 0xfffff500
	s_movk_i32 s2, 0xf0
	s_cselect_b32 s2, s2, 0xf8
	s_add_u32 s2, s90, s2
	s_addc_u32 s3, s91, 0
	s_ashr_i32 s9, s4, 31
	s_lshr_b32 s9, s9, 28
	s_add_i32 s9, s4, s9
	s_ashr_i32 s10, s9, 4
	v_mbcnt_lo_u32_b32 v0, -1, 0
	v_mbcnt_hi_u32_b32 v0, -1, v0
	s_lshl_b32 s11, s10, 10
	v_add_u32_e32 v3, s95, v0
	s_lshl_b32 s4, s4, 6
	s_load_dwordx2 s[2:3], s[2:3], 0x0
	s_lshl_b32 s9, s10, 6
	s_sub_i32 s4, s4, s11
	v_bfe_i32 v1, v3, 4, 1
	s_lshl_b32 s11, s10, 5
	v_lshlrev_b32_e32 v4, 1, v3
	s_lshl_b32 s10, s10, 1
	v_and_b32_e32 v2, 63, v3
	v_and_b32_e32 v1, 0xb00, v1
	s_and_b32 s11, s11, 0xffffff80
	v_and_b32_e32 v4, 24, v4
	s_and_b32 s10, s10, 4
	v_and_b32_e32 v5, 3, v3
	v_bitop3_b32 v0, s9, v208, v2 bitop3:0xc8
	v_add_u32_e32 v1, s11, v1
	v_or3_b32 v4, v4, v5, s10
	v_or3_b32 v176, v4, v0, v1
	s_mov_b32 s5, 0
	v_cmp_lt_i32_e32 vcc, -1, v1
	v_lshl_add_u64 v[0:1], v[176:177], 2, s[6:7]
	v_lshl_add_u32 v2, v2, 2, s52
	v_readlane_b32 s13, v246, 7
	v_readlane_b32 s14, v246, 8
	v_readlane_b32 s15, v246, 9
	v_readlane_b32 s16, v246, 10
	v_readlane_b32 s17, v246, 11
	v_readlane_b32 s18, v246, 12
	v_readlane_b32 s19, v246, 13
	v_readlane_b32 s20, v246, 14
	v_readlane_b32 s21, v246, 15
	v_readlane_b32 s22, v246, 16
	v_readlane_b32 s23, v246, 17
	v_readlane_b32 s24, v246, 18
	v_readlane_b32 s25, v246, 19
	s_waitcnt lgkmcnt(0)
	s_barrier
	v_ashrrev_i32_e32 v30, 6, v3
	v_add_u32_e32 v31, s4, v30
	v_mad_i64_i32 v[26:27], s[10:11], v31, s66, v[0:1]
	v_mad_u64_u32 v[28:29], s[10:11], v30, s56, v[2:3]
	v_mov_b32_e32 v10, 0
	v_mov_b32_e32 v11, 0
	v_mov_b32_e32 v12, 0
	v_mov_b32_e32 v13, 0
	v_mov_b32_e32 v14, 0
	v_mov_b32_e32 v15, 0
	v_mov_b32_e32 v16, 0
	v_mov_b32_e32 v17, 0
	v_mov_b32_e32 v18, 0
	v_mov_b32_e32 v19, 0
	v_mov_b32_e32 v20, 0
	v_mov_b32_e32 v21, 0
	v_mov_b32_e32 v22, 0
	v_mov_b32_e32 v23, 0
	v_mov_b32_e32 v24, 0
	v_mov_b32_e32 v25, 0
	s_lshl_b32 s10, s66, 2
	s_mov_b32 s11, 0
	s_and_saveexec_b64 s[6:7], vcc
	global_load_dword v10, v[26:27], off
	v_lshl_add_u64 v[26:27], v[26:27], 0, s[10:11]
	global_load_dword v11, v[26:27], off
	v_lshl_add_u64 v[26:27], v[26:27], 0, s[10:11]
	global_load_dword v12, v[26:27], off
	v_lshl_add_u64 v[26:27], v[26:27], 0, s[10:11]
	global_load_dword v13, v[26:27], off
	v_lshl_add_u64 v[26:27], v[26:27], 0, s[10:11]
	global_load_dword v14, v[26:27], off
	v_lshl_add_u64 v[26:27], v[26:27], 0, s[10:11]
	global_load_dword v15, v[26:27], off
	v_lshl_add_u64 v[26:27], v[26:27], 0, s[10:11]
	global_load_dword v16, v[26:27], off
	v_lshl_add_u64 v[26:27], v[26:27], 0, s[10:11]
	global_load_dword v17, v[26:27], off
	v_lshl_add_u64 v[26:27], v[26:27], 0, s[10:11]
	global_load_dword v18, v[26:27], off
	v_lshl_add_u64 v[26:27], v[26:27], 0, s[10:11]
	global_load_dword v19, v[26:27], off
	v_lshl_add_u64 v[26:27], v[26:27], 0, s[10:11]
	global_load_dword v20, v[26:27], off
	v_lshl_add_u64 v[26:27], v[26:27], 0, s[10:11]
	global_load_dword v21, v[26:27], off
	v_lshl_add_u64 v[26:27], v[26:27], 0, s[10:11]
	global_load_dword v22, v[26:27], off
	v_lshl_add_u64 v[26:27], v[26:27], 0, s[10:11]
	global_load_dword v23, v[26:27], off
	v_lshl_add_u64 v[26:27], v[26:27], 0, s[10:11]
	global_load_dword v24, v[26:27], off
	v_lshl_add_u64 v[26:27], v[26:27], 0, s[10:11]
	global_load_dword v25, v[26:27], off
	s_or_b64 exec, exec, s[6:7]
	s_waitcnt vmcnt(15)
	ds_write_b32 v28, v10
	s_waitcnt vmcnt(14)
	ds_write_b32 v28, v11 offset:1040
	s_waitcnt vmcnt(13)
	ds_write_b32 v28, v12 offset:2080
	s_waitcnt vmcnt(12)
	ds_write_b32 v28, v13 offset:3120
	s_waitcnt vmcnt(11)
	ds_write_b32 v28, v14 offset:4160
	s_waitcnt vmcnt(10)
	ds_write_b32 v28, v15 offset:5200
	s_waitcnt vmcnt(9)
	ds_write_b32 v28, v16 offset:6240
	s_waitcnt vmcnt(8)
	ds_write_b32 v28, v17 offset:7280
	s_waitcnt vmcnt(7)
	ds_write_b32 v28, v18 offset:8320
	s_waitcnt vmcnt(6)
	ds_write_b32 v28, v19 offset:9360
	s_waitcnt vmcnt(5)
	ds_write_b32 v28, v20 offset:10400
	s_waitcnt vmcnt(4)
	ds_write_b32 v28, v21 offset:11440
	s_waitcnt vmcnt(3)
	ds_write_b32 v28, v22 offset:12480
	s_waitcnt vmcnt(2)
	ds_write_b32 v28, v23 offset:13520
	s_waitcnt vmcnt(1)
	ds_write_b32 v28, v24 offset:14560
	s_waitcnt vmcnt(0)
	ds_write_b32 v28, v25 offset:15600
	s_branch .LBB0_197

; __device__ __forceinline__ void prep_conv_item(const Params& p, int l, int it, char* smem, int wvi) {
;     ...
;   const int ntile = it / KT, ktile = it - ntile * KT;
;   const int n0 = ntile * 64, k0 = ktile * 64;
;   float* sT = reinterpret_cast<float*>(smem);
;   __syncthreads();
; #pragma unroll 4
;   for (int i = 0; i < 16; ++i) {
;     const int idx = tid + 256 * i, k = idx >> 6, n = idx & 63;
;     const int sc = srccol(mode, n0 + n);
;     sT[k * 65 + n] = (sc >= 0) ? src[(size_t)(k0 + k) * ld + sc] : 0.f;
;   }
.LBB0_215:
	v_cvt_f32_ubyte0_e32 v0, s7
	v_rcp_iflag_f32_e32 v0, v0
	s_add_u32 s10, s90, s10
	s_addc_u32 s11, s91, s11
	s_sub_i32 s20, 0, s7
	v_mul_f32_e32 v0, 0x4f7ffffe, v0
	v_cvt_u32_f32_e32 v0, v0
	s_abs_i32 s17, s12
	s_ashr_i32 s13, s12, 31
	v_bfe_i32 v1, v3, 4, 1
	v_readfirstlane_b32 s21, v0
	s_mul_i32 s20, s20, s21
	s_mul_hi_u32 s20, s21, s20
	s_add_i32 s21, s21, s20
	s_mul_hi_u32 s20, s17, s21
	s_mul_i32 s21, s20, s7
	s_sub_i32 s17, s17, s21
	s_add_i32 s21, s20, 1
	s_sub_i32 s22, s17, s7
	s_cmp_ge_u32 s17, s7
	s_cselect_b32 s20, s21, s20
	s_cselect_b32 s17, s22, s17
	s_add_i32 s21, s20, 1
	s_cmp_ge_u32 s17, s7
	s_cselect_b32 s17, s21, s20
	s_xor_b32 s17, s17, s13
	s_sub_i32 s13, s17, s13
	s_mul_i32 s7, s13, s7
	s_lshl_b32 s17, s13, 5
	s_sub_i32 s12, s12, s7
	s_lshl_b32 s7, s13, 6
	v_and_b32_e32 v2, 63, v3
	v_and_b32_e32 v1, 0xb00, v1
	s_and_b32 s17, s17, 0xffffff80
	v_or_b32_e32 v0, s7, v2
	v_add_u32_e32 v1, s17, v1
	s_movk_i32 s17, 0x60
	s_lshl_b32 s13, s13, 1
	v_and_or_b32 v1, v0, s17, v1
	s_and_b32 s13, s13, 4
	v_and_b32_e32 v5, 3, v3
	v_or3_b32 v1, v1, s13, v5
	v_lshrrev_b32_e32 v5, 2, v3
	s_load_dwordx2 s[10:11], s[10:11], 0x0
	v_and_b32_e32 v5, 4, v5
	s_movk_i32 s13, 0xffe3
	v_and_or_b32 v0, v0, s13, v5
	v_lshlrev_b32_e32 v4, 1, v3
	v_cndmask_b32_e64 v0, v1, v0, s[4:5]
	v_and_or_b32 v176, v4, 24, v0
	s_mov_b32 s9, 0
	s_lshl_b32 s12, s12, 6
	v_cmp_lt_i32_e32 vcc, -1, v0
	v_lshl_add_u64 v[0:1], v[176:177], 2, s[14:15]
	v_lshl_add_u32 v2, v2, 2, s52
	s_waitcnt lgkmcnt(0)
	s_barrier
	v_ashrrev_i32_e32 v30, 6, v3
	v_add_u32_e32 v31, s12, v30
	v_mad_i64_i32 v[26:27], s[14:15], s8, v31, 0
	v_lshl_add_u64 v[26:27], v[26:27], 2, v[0:1]
	v_mad_u64_u32 v[28:29], s[14:15], v30, s56, v[2:3]
	v_mov_b32_e32 v10, 0
	v_mov_b32_e32 v11, 0
	v_mov_b32_e32 v12, 0
	v_mov_b32_e32 v13, 0
	v_mov_b32_e32 v14, 0
	v_mov_b32_e32 v15, 0
	v_mov_b32_e32 v16, 0
	v_mov_b32_e32 v17, 0
	v_mov_b32_e32 v18, 0
	v_mov_b32_e32 v19, 0
	v_mov_b32_e32 v20, 0
	v_mov_b32_e32 v21, 0
	v_mov_b32_e32 v22, 0
	v_mov_b32_e32 v23, 0
	v_mov_b32_e32 v24, 0
	v_mov_b32_e32 v25, 0
	s_lshl_b32 s14, s8, 4
	s_mov_b32 s15, 0
	s_and_saveexec_b64 s[4:5], vcc
	global_load_dword v10, v[26:27], off
	v_lshl_add_u64 v[26:27], v[26:27], 0, s[14:15]
	global_load_dword v11, v[26:27], off
	v_lshl_add_u64 v[26:27], v[26:27], 0, s[14:15]
	global_load_dword v12, v[26:27], off
	v_lshl_add_u64 v[26:27], v[26:27], 0, s[14:15]
	global_load_dword v13, v[26:27], off
	v_lshl_add_u64 v[26:27], v[26:27], 0, s[14:15]
	global_load_dword v14, v[26:27], off
	v_lshl_add_u64 v[26:27], v[26:27], 0, s[14:15]
	global_load_dword v15, v[26:27], off
	v_lshl_add_u64 v[26:27], v[26:27], 0, s[14:15]
	global_load_dword v16, v[26:27], off
	v_lshl_add_u64 v[26:27], v[26:27], 0, s[14:15]
	global_load_dword v17, v[26:27], off
	v_lshl_add_u64 v[26:27], v[26:27], 0, s[14:15]
	global_load_dword v18, v[26:27], off
	v_lshl_add_u64 v[26:27], v[26:27], 0, s[14:15]
	global_load_dword v19, v[26:27], off
	v_lshl_add_u64 v[26:27], v[26:27], 0, s[14:15]
	global_load_dword v20, v[26:27], off
	v_lshl_add_u64 v[26:27], v[26:27], 0, s[14:15]
	global_load_dword v21, v[26:27], off
	v_lshl_add_u64 v[26:27], v[26:27], 0, s[14:15]
	global_load_dword v22, v[26:27], off
	v_lshl_add_u64 v[26:27], v[26:27], 0, s[14:15]
	global_load_dword v23, v[26:27], off
	v_lshl_add_u64 v[26:27], v[26:27], 0, s[14:15]
	global_load_dword v24, v[26:27], off
	v_lshl_add_u64 v[26:27], v[26:27], 0, s[14:15]
	global_load_dword v25, v[26:27], off
	s_or_b64 exec, exec, s[4:5]
	s_waitcnt vmcnt(15)
	ds_write_b32 v28, v10
	s_waitcnt vmcnt(14)
	ds_write_b32 v28, v11 offset:1040
	s_waitcnt vmcnt(13)
	ds_write_b32 v28, v12 offset:2080
	s_waitcnt vmcnt(12)
	ds_write_b32 v28, v13 offset:3120
	s_waitcnt vmcnt(11)
	ds_write_b32 v28, v14 offset:4160
	s_waitcnt vmcnt(10)
	ds_write_b32 v28, v15 offset:5200
	s_waitcnt vmcnt(9)
	ds_write_b32 v28, v16 offset:6240
	s_waitcnt vmcnt(8)
	ds_write_b32 v28, v17 offset:7280
	s_waitcnt vmcnt(7)
	ds_write_b32 v28, v18 offset:8320
	s_waitcnt vmcnt(6)
	ds_write_b32 v28, v19 offset:9360
	s_waitcnt vmcnt(5)
	ds_write_b32 v28, v20 offset:10400
	s_waitcnt vmcnt(4)
	ds_write_b32 v28, v21 offset:11440
	s_waitcnt vmcnt(3)
	ds_write_b32 v28, v22 offset:12480
	s_waitcnt vmcnt(2)
	ds_write_b32 v28, v23 offset:13520
	s_waitcnt vmcnt(1)
	ds_write_b32 v28, v24 offset:14560
	s_waitcnt vmcnt(0)
	ds_write_b32 v28, v25 offset:15600
	s_branch .LBB0_211

; __device__ __forceinline__ int srccol(int mode, int n) {
;     ...
;   const int L = (n & ~31) + perm32(n & 31);
;   if (L < 2304) return L;
;   if (L < 3072) return L + 16;
;   if (L < 3088) return L - 768;
;   return -1;
; }
; __device__ __forceinline__ void prep_conv_item(const Params& p, int l, int it, char* smem, int wvi) {
;     ...
;   const int ntile = it / KT, ktile = it - ntile * KT;
;   const int n0 = ntile * 64, k0 = ktile * 64;
;   float* sT = reinterpret_cast<float*>(smem);
;   __syncthreads();
.LBB0_234:
	v_cvt_f32_u32_e32 v2, s21
	s_add_u32 s2, s90, s2
	s_addc_u32 s3, s91, s3
	s_sub_i32 s13, 0, s21
	v_rcp_iflag_f32_e32 v2, v2
	s_abs_i32 s12, s17
	s_ashr_i32 s8, s17, 31
	v_bfe_i32 v5, v3, 4, 1
	v_mul_f32_e32 v2, 0x4f7ffffe, v2
	v_cvt_u32_f32_e32 v2, v2
	v_and_b32_e32 v5, 0xb00, v5
	v_lshlrev_b32_e32 v6, 1, v3
	v_and_b32_e32 v6, 24, v6
	v_readfirstlane_b32 s22, v2
	s_mul_i32 s13, s13, s22
	s_mul_hi_u32 s13, s22, s13
	s_add_i32 s22, s22, s13
	s_mul_hi_u32 s13, s12, s22
	s_mul_i32 s22, s13, s21
	s_sub_i32 s12, s12, s22
	s_add_i32 s23, s13, 1
	s_sub_i32 s22, s12, s21
	s_cmp_ge_u32 s12, s21
	s_cselect_b32 s13, s23, s13
	s_cselect_b32 s12, s22, s12
	s_add_i32 s22, s13, 1
	s_cmp_ge_u32 s12, s21
	s_cselect_b32 s12, s22, s13
	s_xor_b32 s12, s12, s8
	s_sub_i32 s12, s12, s8
	s_mul_i32 s8, s12, s21
	s_lshl_b32 s13, s12, 5
	s_sub_i32 s8, s17, s8
	s_lshl_b32 s17, s12, 6
	v_and_b32_e32 v2, 63, v3
	s_and_b32 s13, s13, 0xffffff80
	s_lshl_b32 s12, s12, 1
	v_bitop3_b32 v4, s17, v208, v2 bitop3:0xc8
	v_add_u32_e32 v5, s13, v5
	s_and_b32 s12, s12, 4
	v_or3_b32 v4, v5, v4, s12
	v_and_b32_e32 v5, 3, v3
	v_or3_b32 v4, v4, v5, v6
	v_lshrrev_b32_e32 v5, 2, v3
	v_and_b32_e32 v5, 4, v5
	v_bitop3_b32 v7, s17, v209, v2 bitop3:0xc8
	s_load_dwordx2 s[2:3], s[2:3], 0x0
	s_lshl_b32 s8, s8, 6
	v_or3_b32 v5, v5, v7, v6
	s_movk_i32 s12, 0xc10
	s_cmpk_lt_u32 s17, 0xc00
	v_add_u32_e32 v6, 0xfffffd00, v5
	v_cmp_gt_u32_e32 vcc, s12, v5
	v_add_u32_e32 v7, 16, v5
	s_movk_i32 s12, 0x900
	v_cndmask_b32_e32 v6, -1, v6, vcc
	s_cselect_b64 vcc, -1, 0
	v_cndmask_b32_e32 v6, v6, v7, vcc
	v_cmp_gt_i32_e32 vcc, s12, v5
	s_mov_b32 s20, 0
	v_lshl_add_u32 v2, v2, 2, s52
	v_cndmask_b32_e32 v6, v6, v5, vcc
	s_waitcnt lgkmcnt(0)
	s_barrier
	s_cmp_lt_i32 s9, 1
	v_mov_b32_e32 v176, v5
	s_cbranch_scc1 .LBB0_241
	s_cmp_lg_u32 s9, 1
	s_mov_b64 s[12:13], -1
	s_cbranch_scc0 .LBB0_239
	s_mov_b64 s[12:13], 0

; __device__ __forceinline__ void prep_conv_item(const Params& p, int l, int it, char* smem, int wvi) {
;     ...
; #pragma unroll 4
;   for (int i = 0; i < 16; ++i) {
;     const int idx = tid + 256 * i, k = idx >> 6, n = idx & 63;
;     const int sc = srccol(mode, n0 + n);
;     sT[k * 65 + n] = (sc >= 0) ? src[(size_t)(k0 + k) * ld + sc] : 0.f;
;   }
.LBB0_241:
	v_ashrrev_i32_e32 v30, 6, v3
	v_add_u32_e32 v31, s8, v30
	v_ashrrev_i32_e32 v32, 31, v31
	v_mul_lo_u32 v33, s10, v32
	v_mul_lo_u32 v34, s11, v31
	v_mad_u64_u32 v[26:27], s[22:23], s10, v31, 0
	v_add3_u32 v27, v27, v33, v34
	v_lshl_add_u64 v[26:27], v[26:27], 2, v[0:1]
	v_lshl_add_u64 v[26:27], v[176:177], 2, v[26:27]
	v_mad_u64_u32 v[28:29], s[22:23], v30, s56, v[2:3]
	v_mov_b32_e32 v10, 0
	v_mov_b32_e32 v11, 0
	v_mov_b32_e32 v12, 0
	v_mov_b32_e32 v13, 0
	v_mov_b32_e32 v14, 0
	v_mov_b32_e32 v15, 0
	v_mov_b32_e32 v16, 0
	v_mov_b32_e32 v17, 0
	v_mov_b32_e32 v18, 0
	v_mov_b32_e32 v19, 0
	v_mov_b32_e32 v20, 0
	v_mov_b32_e32 v21, 0
	v_mov_b32_e32 v22, 0
	v_mov_b32_e32 v23, 0
	v_mov_b32_e32 v24, 0
	v_mov_b32_e32 v25, 0
	v_cmp_lt_i32_e32 vcc, -1, v176
	s_lshl_b64 s[22:23], s[10:11], 4
	s_and_saveexec_b64 s[12:13], vcc
	global_load_dword v10, v[26:27], off
	v_lshl_add_u64 v[26:27], v[26:27], 0, s[22:23]
	global_load_dword v11, v[26:27], off
	v_lshl_add_u64 v[26:27], v[26:27], 0, s[22:23]
	global_load_dword v12, v[26:27], off
	v_lshl_add_u64 v[26:27], v[26:27], 0, s[22:23]
	global_load_dword v13, v[26:27], off
	v_lshl_add_u64 v[26:27], v[26:27], 0, s[22:23]
	global_load_dword v14, v[26:27], off
	v_lshl_add_u64 v[26:27], v[26:27], 0, s[22:23]
	global_load_dword v15, v[26:27], off
	v_lshl_add_u64 v[26:27], v[26:27], 0, s[22:23]
	global_load_dword v16, v[26:27], off
	v_lshl_add_u64 v[26:27], v[26:27], 0, s[22:23]
	global_load_dword v17, v[26:27], off
	v_lshl_add_u64 v[26:27], v[26:27], 0, s[22:23]
	global_load_dword v18, v[26:27], off
	v_lshl_add_u64 v[26:27], v[26:27], 0, s[22:23]
	global_load_dword v19, v[26:27], off
	v_lshl_add_u64 v[26:27], v[26:27], 0, s[22:23]
	global_load_dword v20, v[26:27], off
	v_lshl_add_u64 v[26:27], v[26:27], 0, s[22:23]
	global_load_dword v21, v[26:27], off
	v_lshl_add_u64 v[26:27], v[26:27], 0, s[22:23]
	global_load_dword v22, v[26:27], off
	v_lshl_add_u64 v[26:27], v[26:27], 0, s[22:23]
	global_load_dword v23, v[26:27], off
	v_lshl_add_u64 v[26:27], v[26:27], 0, s[22:23]
	global_load_dword v24, v[26:27], off
	v_lshl_add_u64 v[26:27], v[26:27], 0, s[22:23]
	global_load_dword v25, v[26:27], off
	s_or_b64 exec, exec, s[12:13]
	s_waitcnt vmcnt(15)
	ds_write_b32 v28, v10
	s_waitcnt vmcnt(14)
	ds_write_b32 v28, v11 offset:1040
	s_waitcnt vmcnt(13)
	ds_write_b32 v28, v12 offset:2080
	s_waitcnt vmcnt(12)
	ds_write_b32 v28, v13 offset:3120
	s_waitcnt vmcnt(11)
	ds_write_b32 v28, v14 offset:4160
	s_waitcnt vmcnt(10)
	ds_write_b32 v28, v15 offset:5200
	s_waitcnt vmcnt(9)
	ds_write_b32 v28, v16 offset:6240
	s_waitcnt vmcnt(8)
	ds_write_b32 v28, v17 offset:7280
	s_waitcnt vmcnt(7)
	ds_write_b32 v28, v18 offset:8320
	s_waitcnt vmcnt(6)
	ds_write_b32 v28, v19 offset:9360
	s_waitcnt vmcnt(5)
	ds_write_b32 v28, v20 offset:10400
	s_waitcnt vmcnt(4)
	ds_write_b32 v28, v21 offset:11440
	s_waitcnt vmcnt(3)
	ds_write_b32 v28, v22 offset:12480
	s_waitcnt vmcnt(2)
	ds_write_b32 v28, v23 offset:13520
	s_waitcnt vmcnt(1)
	ds_write_b32 v28, v24 offset:14560
	s_waitcnt vmcnt(0)
	ds_write_b32 v28, v25 offset:15600
	s_branch .LBB0_228

; __device__ __forceinline__ int srccol(int mode, int n) {
;     ...
;   const int L = (n & ~31) + perm32(n & 31);
;   if (L < 2304) return L;
;   if (L < 3072) return L + 16;
;   if (L < 3088) return L - 768;
;   return -1;
; }
; __device__ __forceinline__ void prep_conv_item(const Params& p, int l, int it, char* smem, int wvi) {
;     ...
;   const int ntile = it / KT, ktile = it - ntile * KT;
;   const int n0 = ntile * 64, k0 = ktile * 64;
;   float* sT = reinterpret_cast<float*>(smem);
;   __syncthreads();
.LBB0_277:
	v_cvt_f32_u32_e32 v2, s20
	s_add_u32 s2, s90, s2
	s_addc_u32 s3, s91, s3
	s_sub_i32 s15, 0, s20
	v_rcp_iflag_f32_e32 v2, v2
	s_abs_i32 s14, s16
	s_ashr_i32 s10, s16, 31
	v_bfe_i32 v5, v3, 4, 1
	v_mul_f32_e32 v2, 0x4f7ffffe, v2
	v_cvt_u32_f32_e32 v2, v2
	v_and_b32_e32 v5, 0xb00, v5
	v_lshlrev_b32_e32 v6, 1, v3
	v_and_b32_e32 v6, 24, v6
	v_readfirstlane_b32 s21, v2
	s_mul_i32 s15, s15, s21
	s_mul_hi_u32 s15, s21, s15
	s_add_i32 s21, s21, s15
	s_mul_hi_u32 s15, s14, s21
	s_mul_i32 s21, s15, s20
	s_sub_i32 s14, s14, s21
	s_add_i32 s22, s15, 1
	s_sub_i32 s21, s14, s20
	s_cmp_ge_u32 s14, s20
	s_cselect_b32 s15, s22, s15
	s_cselect_b32 s14, s21, s14
	s_add_i32 s21, s15, 1
	s_cmp_ge_u32 s14, s20
	s_cselect_b32 s14, s21, s15
	s_xor_b32 s14, s14, s10
	s_sub_i32 s14, s14, s10
	s_mul_i32 s10, s14, s20
	s_lshl_b32 s15, s14, 5
	s_sub_i32 s10, s16, s10
	s_lshl_b32 s16, s14, 6
	v_and_b32_e32 v2, 63, v3
	s_and_b32 s15, s15, 0xffffff80
	s_lshl_b32 s14, s14, 1
	v_bitop3_b32 v4, s16, v208, v2 bitop3:0xc8
	v_add_u32_e32 v5, s15, v5
	s_and_b32 s14, s14, 4
	v_or3_b32 v4, v5, v4, s14
	v_and_b32_e32 v5, 3, v3
	v_or3_b32 v4, v4, v5, v6
	v_lshrrev_b32_e32 v5, 2, v3
	v_and_b32_e32 v5, 4, v5
	v_bitop3_b32 v7, s16, v209, v2 bitop3:0xc8
	s_load_dwordx2 s[2:3], s[2:3], 0x0
	s_lshl_b32 s10, s10, 6
	v_or3_b32 v5, v5, v7, v6
	s_movk_i32 s14, 0xc10
	s_cmpk_lt_u32 s16, 0xc00
	v_add_u32_e32 v6, 0xfffffd00, v5
	v_cmp_gt_u32_e32 vcc, s14, v5
	v_add_u32_e32 v7, 16, v5
	s_movk_i32 s14, 0x900
	v_cndmask_b32_e32 v6, -1, v6, vcc
	s_cselect_b64 vcc, -1, 0
	v_cndmask_b32_e32 v6, v6, v7, vcc
	v_cmp_gt_i32_e32 vcc, s14, v5
	s_mov_b32 s17, 0
	v_lshl_add_u32 v2, v2, 2, s52
	v_cndmask_b32_e32 v6, v6, v5, vcc
	s_waitcnt lgkmcnt(0)
	s_barrier
	s_cmp_lt_i32 s11, 1
	v_mov_b32_e32 v176, v5
	s_cbranch_scc1 .LBB0_284
	s_cmp_lg_u32 s11, 1
	s_mov_b64 s[14:15], -1
	s_cbranch_scc0 .LBB0_282
	s_mov_b64 s[14:15], 0

; __device__ __forceinline__ void prep_conv_item(const Params& p, int l, int it, char* smem, int wvi) {
;     ...
; #pragma unroll 4
;   for (int i = 0; i < 16; ++i) {
;     const int idx = tid + 256 * i, k = idx >> 6, n = idx & 63;
;     const int sc = srccol(mode, n0 + n);
;     sT[k * 65 + n] = (sc >= 0) ? src[(size_t)(k0 + k) * ld + sc] : 0.f;
;   }
.LBB0_284:
	v_ashrrev_i32_e32 v30, 6, v3
	v_add_u32_e32 v31, s10, v30
	v_ashrrev_i32_e32 v32, 31, v31
	v_mul_lo_u32 v33, s12, v32
	v_mul_lo_u32 v34, s13, v31
	v_mad_u64_u32 v[26:27], s[20:21], s12, v31, 0
	v_add3_u32 v27, v27, v33, v34
	v_lshl_add_u64 v[26:27], v[26:27], 2, v[0:1]
	v_lshl_add_u64 v[26:27], v[176:177], 2, v[26:27]
	v_mad_u64_u32 v[28:29], s[20:21], v30, s56, v[2:3]
	v_mov_b32_e32 v10, 0
	v_mov_b32_e32 v11, 0
	v_mov_b32_e32 v12, 0
	v_mov_b32_e32 v13, 0
	v_mov_b32_e32 v14, 0
	v_mov_b32_e32 v15, 0
	v_mov_b32_e32 v16, 0
	v_mov_b32_e32 v17, 0
	v_mov_b32_e32 v18, 0
	v_mov_b32_e32 v19, 0
	v_mov_b32_e32 v20, 0
	v_mov_b32_e32 v21, 0
	v_mov_b32_e32 v22, 0
	v_mov_b32_e32 v23, 0
	v_mov_b32_e32 v24, 0
	v_mov_b32_e32 v25, 0
	v_cmp_lt_i32_e32 vcc, -1, v176
	s_lshl_b64 s[20:21], s[12:13], 4
	s_and_saveexec_b64 s[14:15], vcc
	global_load_dword v10, v[26:27], off
	v_lshl_add_u64 v[26:27], v[26:27], 0, s[20:21]
	global_load_dword v11, v[26:27], off
	v_lshl_add_u64 v[26:27], v[26:27], 0, s[20:21]
	global_load_dword v12, v[26:27], off
	v_lshl_add_u64 v[26:27], v[26:27], 0, s[20:21]
	global_load_dword v13, v[26:27], off
	v_lshl_add_u64 v[26:27], v[26:27], 0, s[20:21]
	global_load_dword v14, v[26:27], off
	v_lshl_add_u64 v[26:27], v[26:27], 0, s[20:21]
	global_load_dword v15, v[26:27], off
	v_lshl_add_u64 v[26:27], v[26:27], 0, s[20:21]
	global_load_dword v16, v[26:27], off
	v_lshl_add_u64 v[26:27], v[26:27], 0, s[20:21]
	global_load_dword v17, v[26:27], off
	v_lshl_add_u64 v[26:27], v[26:27], 0, s[20:21]
	global_load_dword v18, v[26:27], off
	v_lshl_add_u64 v[26:27], v[26:27], 0, s[20:21]
	global_load_dword v19, v[26:27], off
	v_lshl_add_u64 v[26:27], v[26:27], 0, s[20:21]
	global_load_dword v20, v[26:27], off
	v_lshl_add_u64 v[26:27], v[26:27], 0, s[20:21]
	global_load_dword v21, v[26:27], off
	v_lshl_add_u64 v[26:27], v[26:27], 0, s[20:21]
	global_load_dword v22, v[26:27], off
	v_lshl_add_u64 v[26:27], v[26:27], 0, s[20:21]
	global_load_dword v23, v[26:27], off
	v_lshl_add_u64 v[26:27], v[26:27], 0, s[20:21]
	global_load_dword v24, v[26:27], off
	v_lshl_add_u64 v[26:27], v[26:27], 0, s[20:21]
	global_load_dword v25, v[26:27], off
	s_or_b64 exec, exec, s[14:15]
	s_waitcnt vmcnt(15)
	ds_write_b32 v28, v10
	s_waitcnt vmcnt(14)
	ds_write_b32 v28, v11 offset:1040
	s_waitcnt vmcnt(13)
	ds_write_b32 v28, v12 offset:2080
	s_waitcnt vmcnt(12)
	ds_write_b32 v28, v13 offset:3120
	s_waitcnt vmcnt(11)
	ds_write_b32 v28, v14 offset:4160
	s_waitcnt vmcnt(10)
	ds_write_b32 v28, v15 offset:5200
	s_waitcnt vmcnt(9)
	ds_write_b32 v28, v16 offset:6240
	s_waitcnt vmcnt(8)
	ds_write_b32 v28, v17 offset:7280
	s_waitcnt vmcnt(7)
	ds_write_b32 v28, v18 offset:8320
	s_waitcnt vmcnt(6)
	ds_write_b32 v28, v19 offset:9360
	s_waitcnt vmcnt(5)
	ds_write_b32 v28, v20 offset:10400
	s_waitcnt vmcnt(4)
	ds_write_b32 v28, v21 offset:11440
	s_waitcnt vmcnt(3)
	ds_write_b32 v28, v22 offset:12480
	s_waitcnt vmcnt(2)
	ds_write_b32 v28, v23 offset:13520
	s_waitcnt vmcnt(1)
	ds_write_b32 v28, v24 offset:14560
	s_waitcnt vmcnt(0)
	ds_write_b32 v28, v25 offset:15600
	s_branch .LBB0_268

; __device__ __forceinline__ bf16_t f2bf(float f) { return (bf16_t)(pk2(f, 0.f) & 0xffffu); }
; __device__ __forceinline__ void hy_lat_item(const Params& p, int l, int o, int item, char* smem, int wvi) {
;     ...
;   __syncthreads();
;   for (int q = tid; q < 8192; q += 256) {
;     const bf16_t r = (q == 0) ? (bf16_t)0 : f2bf(kf[8192 - q]);
;     sE[q] = r;
;     if (q >= 1) sO[q - 1] = r;
;   }
;   if (tid == 0) sO[8191] = 0;
;   if (tid < 36) reinterpret_cast<unsigned*>(sZ + 4 * 4608)[tid] = 0u;
.LBB0_393:
	s_cmp_ge_i32 s13, s12
	s_mov_b64 s[2:3], -1
	s_cbranch_scc0 .LBB0_420
	s_sub_i32 s0, s13, s12
	s_lshr_b32 s10, s0, 2
	v_readlane_b32 s0, v245, 47
	v_readlane_b32 s1, v245, 48
	s_add_i32 s0, s10, 0x100
	v_writelane_b32 v245, s0, 47
	s_waitcnt vmcnt(1)
	v_mbcnt_lo_u32_b32 v0, -1, 0
	v_mbcnt_hi_u32_b32 v0, -1, v0
	s_nop 0
	v_add_u32_e32 v1, s95, v0
	v_writelane_b32 v245, s1, 48
	s_movk_i32 s0, 0x2000
	s_nop 0
	v_cmp_gt_i32_e32 vcc, s0, v1
	s_barrier
	s_and_saveexec_b64 s[2:3], vcc
	s_cbranch_execz .LBB0_401
	v_readlane_b32 s0, v245, 47
	v_readlane_b32 s1, v245, 48
	v_readlane_b32 s20, v245, 51
	s_lshl_b64 s[0:1], s[0:1], 15
	v_readlane_b32 s22, v245, 53
	v_readlane_b32 s23, v245, 54
	s_add_u32 s4, s22, s0
	s_addc_u32 s5, s23, s1
	v_sub_u32_e32 v176, 0x2000, v1
	v_lshl_add_u32 v0, v1, 1, s52
	s_mov_b64 s[6:7], 0
	v_mov_b32_e32 v2, v1
	v_readlane_b32 s21, v245, 52
	v_readlane_b32 s24, v245, 55
	v_readlane_b32 s25, v245, 56
	v_readlane_b32 s26, v245, 57
	v_readlane_b32 s27, v245, 58
	v_lshlrev_b32_e32 v4, 2, v176
	v_mov_b32_e32 v6, 0
	v_cmp_ne_u32_e32 vcc, 0, v1
	s_mov_b64 s[6:7], s[4:5]
	s_and_saveexec_b64 s[8:9], vcc
	global_load_dword v6, v4, s[6:7]
	s_or_b64 exec, exec, s[8:9]
	global_load_dword v7, v4, s[6:7] offset:-1024
	global_load_dword v8, v4, s[6:7] offset:-2048
	global_load_dword v9, v4, s[6:7] offset:-3072
	s_sub_u32 s6, s6, 0x1000
	s_subb_u32 s7, s7, 0
	global_load_dword v10, v4, s[6:7]
	global_load_dword v11, v4, s[6:7] offset:-1024
	global_load_dword v12, v4, s[6:7] offset:-2048
	global_load_dword v13, v4, s[6:7] offset:-3072
	s_sub_u32 s6, s6, 0x1000
	s_subb_u32 s7, s7, 0
	global_load_dword v14, v4, s[6:7]
	global_load_dword v15, v4, s[6:7] offset:-1024
	global_load_dword v16, v4, s[6:7] offset:-2048
	global_load_dword v17, v4, s[6:7] offset:-3072
	s_sub_u32 s6, s6, 0x1000
	s_subb_u32 s7, s7, 0
	global_load_dword v18, v4, s[6:7]
	global_load_dword v19, v4, s[6:7] offset:-1024
	global_load_dword v20, v4, s[6:7] offset:-2048
	global_load_dword v21, v4, s[6:7] offset:-3072
	s_sub_u32 s6, s6, 0x1000
	s_subb_u32 s7, s7, 0
	global_load_dword v22, v4, s[6:7]
	global_load_dword v23, v4, s[6:7] offset:-1024
	global_load_dword v24, v4, s[6:7] offset:-2048
	global_load_dword v25, v4, s[6:7] offset:-3072
	s_sub_u32 s6, s6, 0x1000
	s_subb_u32 s7, s7, 0
	global_load_dword v26, v4, s[6:7]
	global_load_dword v27, v4, s[6:7] offset:-1024
	global_load_dword v28, v4, s[6:7] offset:-2048
	global_load_dword v29, v4, s[6:7] offset:-3072
	s_sub_u32 s6, s6, 0x1000
	s_subb_u32 s7, s7, 0
	global_load_dword v30, v4, s[6:7]
	global_load_dword v31, v4, s[6:7] offset:-1024
	global_load_dword v32, v4, s[6:7] offset:-2048
	global_load_dword v33, v4, s[6:7] offset:-3072
	s_sub_u32 s6, s6, 0x1000
	s_subb_u32 s7, s7, 0
	global_load_dword v34, v4, s[6:7]
	global_load_dword v35, v4, s[6:7] offset:-1024
	global_load_dword v36, v4, s[6:7] offset:-2048
	global_load_dword v37, v4, s[6:7] offset:-3072
	s_waitcnt vmcnt(31)
	v_cvt_pk_bf16_f32 v6, v6, v6
	ds_write_b16 v0, v6
	v_cmp_lt_i32_e32 vcc, 0, v1
	s_and_saveexec_b64 s[8:9], vcc
	ds_write_b16 v0, v6 offset:16446
	s_or_b64 exec, exec, s[8:9]
	s_waitcnt vmcnt(30)
	v_cvt_pk_bf16_f32 v7, v7, v7
	ds_write_b16 v0, v7 offset:512
	ds_write_b16 v0, v7 offset:16958
	s_waitcnt vmcnt(29)
	v_cvt_pk_bf16_f32 v8, v8, v8
	ds_write_b16 v0, v8 offset:1024
	ds_write_b16 v0, v8 offset:17470
	s_waitcnt vmcnt(28)
	v_cvt_pk_bf16_f32 v9, v9, v9
	ds_write_b16 v0, v9 offset:1536
	ds_write_b16 v0, v9 offset:17982
	s_waitcnt vmcnt(27)
	v_cvt_pk_bf16_f32 v10, v10, v10
	ds_write_b16 v0, v10 offset:2048
	ds_write_b16 v0, v10 offset:18494
	s_waitcnt vmcnt(26)
	v_cvt_pk_bf16_f32 v11, v11, v11
	ds_write_b16 v0, v11 offset:2560
	ds_write_b16 v0, v11 offset:19006
	s_waitcnt vmcnt(25)
	v_cvt_pk_bf16_f32 v12, v12, v12
	ds_write_b16 v0, v12 offset:3072
	ds_write_b16 v0, v12 offset:19518
	s_waitcnt vmcnt(24)
	v_cvt_pk_bf16_f32 v13, v13, v13
	ds_write_b16 v0, v13 offset:3584
	ds_write_b16 v0, v13 offset:20030
	s_waitcnt vmcnt(23)
	v_cvt_pk_bf16_f32 v14, v14, v14
	ds_write_b16 v0, v14 offset:4096
	ds_write_b16 v0, v14 offset:20542
	s_waitcnt vmcnt(22)
	v_cvt_pk_bf16_f32 v15, v15, v15
	ds_write_b16 v0, v15 offset:4608
	ds_write_b16 v0, v15 offset:21054
	s_waitcnt vmcnt(21)
	v_cvt_pk_bf16_f32 v16, v16, v16
	ds_write_b16 v0, v16 offset:5120
	ds_write_b16 v0, v16 offset:21566
	s_waitcnt vmcnt(20)
	v_cvt_pk_bf16_f32 v17, v17, v17
	ds_write_b16 v0, v17 offset:5632
	ds_write_b16 v0, v17 offset:22078
	s_waitcnt vmcnt(19)
	v_cvt_pk_bf16_f32 v18, v18, v18
	ds_write_b16 v0, v18 offset:6144
	ds_write_b16 v0, v18 offset:22590
	s_waitcnt vmcnt(18)
	v_cvt_pk_bf16_f32 v19, v19, v19
	ds_write_b16 v0, v19 offset:6656
	ds_write_b16 v0, v19 offset:23102
	s_waitcnt vmcnt(17)
	v_cvt_pk_bf16_f32 v20, v20, v20
	ds_write_b16 v0, v20 offset:7168
	ds_write_b16 v0, v20 offset:23614
	s_waitcnt vmcnt(16)
	v_cvt_pk_bf16_f32 v21, v21, v21
	ds_write_b16 v0, v21 offset:7680
	ds_write_b16 v0, v21 offset:24126
	s_waitcnt vmcnt(15)
	v_cvt_pk_bf16_f32 v22, v22, v22
	ds_write_b16 v0, v22 offset:8192
	ds_write_b16 v0, v22 offset:24638
	s_waitcnt vmcnt(14)
	v_cvt_pk_bf16_f32 v23, v23, v23
	ds_write_b16 v0, v23 offset:8704
	ds_write_b16 v0, v23 offset:25150
	s_waitcnt vmcnt(13)
	v_cvt_pk_bf16_f32 v24, v24, v24
	ds_write_b16 v0, v24 offset:9216
	ds_write_b16 v0, v24 offset:25662
	s_waitcnt vmcnt(12)
	v_cvt_pk_bf16_f32 v25, v25, v25
	ds_write_b16 v0, v25 offset:9728
	ds_write_b16 v0, v25 offset:26174
	s_waitcnt vmcnt(11)
	v_cvt_pk_bf16_f32 v26, v26, v26
	ds_write_b16 v0, v26 offset:10240
	ds_write_b16 v0, v26 offset:26686
	s_waitcnt vmcnt(10)
	v_cvt_pk_bf16_f32 v27, v27, v27
	ds_write_b16 v0, v27 offset:10752
	ds_write_b16 v0, v27 offset:27198
	s_waitcnt vmcnt(9)
	v_cvt_pk_bf16_f32 v28, v28, v28
	ds_write_b16 v0, v28 offset:11264
	ds_write_b16 v0, v28 offset:27710
	s_waitcnt vmcnt(8)
	v_cvt_pk_bf16_f32 v29, v29, v29
	ds_write_b16 v0, v29 offset:11776
	ds_write_b16 v0, v29 offset:28222
	s_waitcnt vmcnt(7)
	v_cvt_pk_bf16_f32 v30, v30, v30
	ds_write_b16 v0, v30 offset:12288
	ds_write_b16 v0, v30 offset:28734
	s_waitcnt vmcnt(6)
	v_cvt_pk_bf16_f32 v31, v31, v31
	ds_write_b16 v0, v31 offset:12800
	ds_write_b16 v0, v31 offset:29246
	s_waitcnt vmcnt(5)
	v_cvt_pk_bf16_f32 v32, v32, v32
	ds_write_b16 v0, v32 offset:13312
	ds_write_b16 v0, v32 offset:29758
	s_waitcnt vmcnt(4)
	v_cvt_pk_bf16_f32 v33, v33, v33
	ds_write_b16 v0, v33 offset:13824
	ds_write_b16 v0, v33 offset:30270
	s_waitcnt vmcnt(3)
	v_cvt_pk_bf16_f32 v34, v34, v34
	ds_write_b16 v0, v34 offset:14336
	ds_write_b16 v0, v34 offset:30782
	s_waitcnt vmcnt(2)
	v_cvt_pk_bf16_f32 v35, v35, v35
	ds_write_b16 v0, v35 offset:14848
	ds_write_b16 v0, v35 offset:31294
	s_waitcnt vmcnt(1)
	v_cvt_pk_bf16_f32 v36, v36, v36
	ds_write_b16 v0, v36 offset:15360
	ds_write_b16 v0, v36 offset:31806
	s_waitcnt vmcnt(0)
	v_cvt_pk_bf16_f32 v37, v37, v37
	ds_write_b16 v0, v37 offset:15872
	ds_write_b16 v0, v37 offset:32318

; __device__ __forceinline__ bf16_t f2bf(float f) { return (bf16_t)(pk2(f, 0.f) & 0xffffu); }
; __device__ __forceinline__ void hy_lat_item(const Params& p, int l, int o, int item, char* smem, int wvi) {
;     ...
;   __syncthreads();
;   for (int q = tid; q < 8192; q += 256) {
;     const bf16_t r = (q == 0) ? (bf16_t)0 : f2bf(kf[8192 - q]);
;     sE[q] = r;
;     if (q >= 1) sO[q - 1] = r;
;   }
;   if (tid == 0) sO[8191] = 0;
;   if (tid < 36) reinterpret_cast<unsigned*>(sZ + 4 * 4608)[tid] = 0u;
.LBB0_463:
	s_cmp_ge_i32 s13, s12
	s_mov_b64 s[2:3], -1
	s_cbranch_scc0 .LBB0_490
	s_sub_i32 s0, s13, s12
	v_readlane_b32 s2, v245, 47
	s_waitcnt vmcnt(1)
	v_mbcnt_lo_u32_b32 v0, -1, 0
	v_mbcnt_hi_u32_b32 v0, -1, v0
	v_readlane_b32 s3, v245, 48
	v_add_u32_e32 v1, s95, v0
	s_lshr_b32 s2, s0, 2
	s_movk_i32 s0, 0x2000
	v_writelane_b32 v245, s2, 47
	v_cmp_gt_i32_e32 vcc, s0, v1
	s_waitcnt lgkmcnt(0)
	v_writelane_b32 v245, s3, 48
	s_barrier
	s_and_saveexec_b64 s[2:3], vcc
	s_cbranch_execz .LBB0_471
	v_readlane_b32 s0, v245, 47
	v_readlane_b32 s1, v245, 48
	v_readlane_b32 s4, v245, 51
	s_lshl_b64 s[0:1], s[0:1], 15
	v_readlane_b32 s6, v245, 53
	v_readlane_b32 s5, v245, 52
	v_readlane_b32 s7, v245, 54
	s_add_u32 s4, s6, s0
	s_addc_u32 s5, s7, s1
	v_sub_u32_e32 v176, 0x2000, v1
	v_lshl_add_u32 v0, v1, 1, s52
	s_mov_b64 s[6:7], 0
	v_mov_b32_e32 v2, v1
	v_readlane_b32 s8, v245, 55
	v_readlane_b32 s9, v245, 56
	v_readlane_b32 s10, v245, 57
	v_readlane_b32 s11, v245, 58
	v_lshlrev_b32_e32 v4, 2, v176
	v_mov_b32_e32 v6, 0
	v_cmp_ne_u32_e32 vcc, 0, v1
	s_mov_b64 s[6:7], s[4:5]
	s_and_saveexec_b64 s[8:9], vcc
	global_load_dword v6, v4, s[6:7]
	s_or_b64 exec, exec, s[8:9]
	global_load_dword v7, v4, s[6:7] offset:-1024
	global_load_dword v8, v4, s[6:7] offset:-2048
	global_load_dword v9, v4, s[6:7] offset:-3072
	s_sub_u32 s6, s6, 0x1000
	s_subb_u32 s7, s7, 0
	global_load_dword v10, v4, s[6:7]
	global_load_dword v11, v4, s[6:7] offset:-1024
	global_load_dword v12, v4, s[6:7] offset:-2048
	global_load_dword v13, v4, s[6:7] offset:-3072
	s_sub_u32 s6, s6, 0x1000
	s_subb_u32 s7, s7, 0
	global_load_dword v14, v4, s[6:7]
	global_load_dword v15, v4, s[6:7] offset:-1024
	global_load_dword v16, v4, s[6:7] offset:-2048
	global_load_dword v17, v4, s[6:7] offset:-3072
	s_sub_u32 s6, s6, 0x1000
	s_subb_u32 s7, s7, 0
	global_load_dword v18, v4, s[6:7]
	global_load_dword v19, v4, s[6:7] offset:-1024
	global_load_dword v20, v4, s[6:7] offset:-2048
	global_load_dword v21, v4, s[6:7] offset:-3072
	s_sub_u32 s6, s6, 0x1000
	s_subb_u32 s7, s7, 0
	global_load_dword v22, v4, s[6:7]
	global_load_dword v23, v4, s[6:7] offset:-1024
	global_load_dword v24, v4, s[6:7] offset:-2048
	global_load_dword v25, v4, s[6:7] offset:-3072
	s_sub_u32 s6, s6, 0x1000
	s_subb_u32 s7, s7, 0
	global_load_dword v26, v4, s[6:7]
	global_load_dword v27, v4, s[6:7] offset:-1024
	global_load_dword v28, v4, s[6:7] offset:-2048
	global_load_dword v29, v4, s[6:7] offset:-3072
	s_sub_u32 s6, s6, 0x1000
	s_subb_u32 s7, s7, 0
	global_load_dword v30, v4, s[6:7]
	global_load_dword v31, v4, s[6:7] offset:-1024
	global_load_dword v32, v4, s[6:7] offset:-2048
	global_load_dword v33, v4, s[6:7] offset:-3072
	s_sub_u32 s6, s6, 0x1000
	s_subb_u32 s7, s7, 0
	global_load_dword v34, v4, s[6:7]
	global_load_dword v35, v4, s[6:7] offset:-1024
	global_load_dword v36, v4, s[6:7] offset:-2048
	global_load_dword v37, v4, s[6:7] offset:-3072
	s_waitcnt vmcnt(31)
	v_cvt_pk_bf16_f32 v6, v6, v6
	ds_write_b16 v0, v6
	v_cmp_lt_i32_e32 vcc, 0, v1
	s_and_saveexec_b64 s[8:9], vcc
	ds_write_b16 v0, v6 offset:16446
	s_or_b64 exec, exec, s[8:9]
	s_waitcnt vmcnt(30)
	v_cvt_pk_bf16_f32 v7, v7, v7
	ds_write_b16 v0, v7 offset:512
	ds_write_b16 v0, v7 offset:16958
	s_waitcnt vmcnt(29)
	v_cvt_pk_bf16_f32 v8, v8, v8
	ds_write_b16 v0, v8 offset:1024
	ds_write_b16 v0, v8 offset:17470
	s_waitcnt vmcnt(28)
	v_cvt_pk_bf16_f32 v9, v9, v9
	ds_write_b16 v0, v9 offset:1536
	ds_write_b16 v0, v9 offset:17982
	s_waitcnt vmcnt(27)
	v_cvt_pk_bf16_f32 v10, v10, v10
	ds_write_b16 v0, v10 offset:2048
	ds_write_b16 v0, v10 offset:18494
	s_waitcnt vmcnt(26)
	v_cvt_pk_bf16_f32 v11, v11, v11
	ds_write_b16 v0, v11 offset:2560
	ds_write_b16 v0, v11 offset:19006
	s_waitcnt vmcnt(25)
	v_cvt_pk_bf16_f32 v12, v12, v12
	ds_write_b16 v0, v12 offset:3072
	ds_write_b16 v0, v12 offset:19518
	s_waitcnt vmcnt(24)
	v_cvt_pk_bf16_f32 v13, v13, v13
	ds_write_b16 v0, v13 offset:3584
	ds_write_b16 v0, v13 offset:20030
	s_waitcnt vmcnt(23)
	v_cvt_pk_bf16_f32 v14, v14, v14
	ds_write_b16 v0, v14 offset:4096
	ds_write_b16 v0, v14 offset:20542
	s_waitcnt vmcnt(22)
	v_cvt_pk_bf16_f32 v15, v15, v15
	ds_write_b16 v0, v15 offset:4608
	ds_write_b16 v0, v15 offset:21054
	s_waitcnt vmcnt(21)
	v_cvt_pk_bf16_f32 v16, v16, v16
	ds_write_b16 v0, v16 offset:5120
	ds_write_b16 v0, v16 offset:21566
	s_waitcnt vmcnt(20)
	v_cvt_pk_bf16_f32 v17, v17, v17
	ds_write_b16 v0, v17 offset:5632
	ds_write_b16 v0, v17 offset:22078
	s_waitcnt vmcnt(19)
	v_cvt_pk_bf16_f32 v18, v18, v18
	ds_write_b16 v0, v18 offset:6144
	ds_write_b16 v0, v18 offset:22590
	s_waitcnt vmcnt(18)
	v_cvt_pk_bf16_f32 v19, v19, v19
	ds_write_b16 v0, v19 offset:6656
	ds_write_b16 v0, v19 offset:23102
	s_waitcnt vmcnt(17)
	v_cvt_pk_bf16_f32 v20, v20, v20
	ds_write_b16 v0, v20 offset:7168
	ds_write_b16 v0, v20 offset:23614
	s_waitcnt vmcnt(16)
	v_cvt_pk_bf16_f32 v21, v21, v21
	ds_write_b16 v0, v21 offset:7680
	ds_write_b16 v0, v21 offset:24126
	s_waitcnt vmcnt(15)
	v_cvt_pk_bf16_f32 v22, v22, v22
	ds_write_b16 v0, v22 offset:8192
	ds_write_b16 v0, v22 offset:24638
	s_waitcnt vmcnt(14)
	v_cvt_pk_bf16_f32 v23, v23, v23
	ds_write_b16 v0, v23 offset:8704
	ds_write_b16 v0, v23 offset:25150
	s_waitcnt vmcnt(13)
	v_cvt_pk_bf16_f32 v24, v24, v24
	ds_write_b16 v0, v24 offset:9216
	ds_write_b16 v0, v24 offset:25662
	s_waitcnt vmcnt(12)
	v_cvt_pk_bf16_f32 v25, v25, v25
	ds_write_b16 v0, v25 offset:9728
	ds_write_b16 v0, v25 offset:26174
	s_waitcnt vmcnt(11)
	v_cvt_pk_bf16_f32 v26, v26, v26
	ds_write_b16 v0, v26 offset:10240
	ds_write_b16 v0, v26 offset:26686
	s_waitcnt vmcnt(10)
	v_cvt_pk_bf16_f32 v27, v27, v27
	ds_write_b16 v0, v27 offset:10752
	ds_write_b16 v0, v27 offset:27198
	s_waitcnt vmcnt(9)
	v_cvt_pk_bf16_f32 v28, v28, v28
	ds_write_b16 v0, v28 offset:11264
	ds_write_b16 v0, v28 offset:27710
	s_waitcnt vmcnt(8)
	v_cvt_pk_bf16_f32 v29, v29, v29
	ds_write_b16 v0, v29 offset:11776
	ds_write_b16 v0, v29 offset:28222
	s_waitcnt vmcnt(7)
	v_cvt_pk_bf16_f32 v30, v30, v30
	ds_write_b16 v0, v30 offset:12288
	ds_write_b16 v0, v30 offset:28734
	s_waitcnt vmcnt(6)
	v_cvt_pk_bf16_f32 v31, v31, v31
	ds_write_b16 v0, v31 offset:12800
	ds_write_b16 v0, v31 offset:29246
	s_waitcnt vmcnt(5)
	v_cvt_pk_bf16_f32 v32, v32, v32
	ds_write_b16 v0, v32 offset:13312
	ds_write_b16 v0, v32 offset:29758
	s_waitcnt vmcnt(4)
	v_cvt_pk_bf16_f32 v33, v33, v33
	ds_write_b16 v0, v33 offset:13824
	ds_write_b16 v0, v33 offset:30270
	s_waitcnt vmcnt(3)
	v_cvt_pk_bf16_f32 v34, v34, v34
	ds_write_b16 v0, v34 offset:14336
	ds_write_b16 v0, v34 offset:30782
	s_waitcnt vmcnt(2)
	v_cvt_pk_bf16_f32 v35, v35, v35
	ds_write_b16 v0, v35 offset:14848
	ds_write_b16 v0, v35 offset:31294
	s_waitcnt vmcnt(1)
	v_cvt_pk_bf16_f32 v36, v36, v36
	ds_write_b16 v0, v36 offset:15360
	ds_write_b16 v0, v36 offset:31806
	s_waitcnt vmcnt(0)
	v_cvt_pk_bf16_f32 v37, v37, v37
	ds_write_b16 v0, v37 offset:15872
	ds_write_b16 v0, v37 offset:32318

; __device__ __forceinline__ u32x4 zero_u4() { unsigned z = 0u; asm volatile("" : "+v"(z)); return (u32x4){z, z, z, z}; }
; __device__ __forceinline__ void conv_hy_item(const Params& p, int l, int item, char* smem, int wvi) {
;     ...
;   __syncthreads();
;   for (int slot = tid; slot < 66 * 32; slot += 256) {
;     const int r = slot >> 5, c8 = slot & 31;
;     const bool valid = (r == 0) ? hasPrev : ((r == 65) ? hasNext : true);
;     u32x4 v = zero_u4();
;     if (valid) v = *reinterpret_cast<const u32x4*>(ph + (size_t)(tok0 - 1 + r) * 768 + c8 * 8);
;     *reinterpret_cast<u32x4*>(sIn + r * 264 + c8 * 8) = v;
;   }
.LBB0_538:
	s_mul_hi_i32 s1, s0, 0x55555556
	s_lshr_b32 s2, s1, 31
	s_add_i32 s1, s1, s2
	s_mul_i32 s2, s1, -3
	s_add_i32 s2, s2, s0
	s_waitcnt vmcnt(1)
	v_mbcnt_lo_u32_b32 v0, -1, 0
	v_mbcnt_hi_u32_b32 v0, -1, v0
	s_lshl_b32 s8, s2, 8
	v_add_u32_e32 v9, s95, v0
	s_movk_i32 s2, 0x840
	s_lshl_b32 s10, s1, 6
	v_cmp_gt_i32_e32 vcc, s2, v9
	s_waitcnt lgkmcnt(0)
	s_barrier
	s_and_saveexec_b64 s[2:3], vcc
	s_cbranch_execz .LBB0_545
	s_cmpk_gt_i32 s0, 0xbff
	s_cselect_b64 s[14:15], -1, 0
	s_and_b32 s1, s1, 3
	s_cmp_lg_u32 s1, 0
	s_cselect_b64 s[16:17], -1, 0
	s_cmp_lg_u32 s1, 3
	s_cselect_b64 s[12:13], -1, 0
	s_ashr_i32 s9, s8, 31
	v_readlane_b32 s36, v246, 63
	s_and_b64 s[12:13], s[14:15], s[12:13]
	s_and_b64 s[14:15], s[14:15], s[16:17]
	s_lshl_b64 s[16:17], s[8:9], 1
	v_readlane_b32 s48, v245, 11
	v_readlane_b32 s49, v245, 12
	s_add_u32 s16, s48, s16
	v_lshlrev_b32_e32 v0, 4, v9
	s_addc_u32 s17, s49, s17
	v_and_b32_e32 v176, 0x1f0, v0
	s_add_i32 s1, s10, -1
	s_waitcnt vmcnt(0)
	v_lshl_add_u64 v[6:7], s[16:17], 0, v[176:177]
	v_add_u32_e32 v8, s52, v176
	s_mov_b64 s[16:17], 0
	v_mov_b32_e32 v5, v9
	v_readlane_b32 s37, v245, 0
	v_readlane_b32 s38, v245, 1
	v_readlane_b32 s39, v245, 2
	v_readlane_b32 s40, v245, 3
	v_readlane_b32 s41, v245, 4
	v_readlane_b32 s42, v245, 5
	v_readlane_b32 s43, v245, 6
	v_readlane_b32 s44, v245, 7
	v_readlane_b32 s45, v245, 8
	v_readlane_b32 s46, v245, 9
	v_readlane_b32 s47, v245, 10
	v_readlane_b32 s50, v245, 13
	v_readlane_b32 s51, v245, 14
	v_ashrrev_i32_e32 v10, 5, v9
	v_add_u32_e32 v0, s1, v10
	s_movk_i32 s5, 0x600
	v_mad_i64_i32 v[12:13], s[20:21], v0, s5, v[6:7]
	s_movk_i32 s5, 0x210
	v_mad_u64_u32 v[14:15], s[20:21], v10, s5, v[8:9]
	s_mov_b64 s[22:23], 0x3000
	v_mov_b32_e32 v16, 0
	v_mov_b32_e32 v17, 0
	v_mov_b32_e32 v18, 0
	v_mov_b32_e32 v19, 0
	v_mov_b32_e32 v48, 0
	v_mov_b32_e32 v49, 0
	v_mov_b32_e32 v50, 0
	v_mov_b32_e32 v51, 0
	v_cmp_lt_u32_e32 vcc, 31, v9
	s_or_b64 s[20:21], vcc, s[14:15]
	s_and_saveexec_b64 s[28:29], s[20:21]
	global_load_dwordx4 v[16:19], v[12:13], off
	s_mov_b64 exec, s[28:29]
	v_lshl_add_u64 v[12:13], v[12:13], 0, s[22:23]
	global_load_dwordx4 v[20:23], v[12:13], off
	v_lshl_add_u64 v[12:13], v[12:13], 0, s[22:23]
	global_load_dwordx4 v[24:27], v[12:13], off
	v_lshl_add_u64 v[12:13], v[12:13], 0, s[22:23]
	global_load_dwordx4 v[28:31], v[12:13], off
	v_lshl_add_u64 v[12:13], v[12:13], 0, s[22:23]
	global_load_dwordx4 v[32:35], v[12:13], off
	v_lshl_add_u64 v[12:13], v[12:13], 0, s[22:23]
	global_load_dwordx4 v[36:39], v[12:13], off
	v_lshl_add_u64 v[12:13], v[12:13], 0, s[22:23]
	global_load_dwordx4 v[40:43], v[12:13], off
	v_lshl_add_u64 v[12:13], v[12:13], 0, s[22:23]
	global_load_dwordx4 v[44:47], v[12:13], off
	v_lshl_add_u64 v[12:13], v[12:13], 0, s[22:23]
	v_cmp_gt_u32_e32 vcc, 32, v9
	s_mov_b64 s[20:21], vcc
	v_cmp_gt_u32_e32 vcc, 64, v9
	s_and_b64 s[28:29], vcc, s[12:13]
	s_or_b64 s[20:21], s[20:21], s[28:29]
	s_and_saveexec_b64 s[28:29], s[20:21]
	global_load_dwordx4 v[48:51], v[12:13], off
	s_mov_b64 exec, s[28:29]
	s_waitcnt vmcnt(8)
	ds_write_b128 v14, v[16:19]
	s_waitcnt vmcnt(7)
	ds_write_b128 v14, v[20:23] offset:4224
	s_waitcnt vmcnt(6)
	ds_write_b128 v14, v[24:27] offset:8448
	s_waitcnt vmcnt(5)
	ds_write_b128 v14, v[28:31] offset:12672
	s_waitcnt vmcnt(4)
	ds_write_b128 v14, v[32:35] offset:16896
	s_waitcnt vmcnt(3)
	ds_write_b128 v14, v[36:39] offset:21120
	s_waitcnt vmcnt(2)
	ds_write_b128 v14, v[40:43] offset:25344
	s_waitcnt vmcnt(1)
	ds_write_b128 v14, v[44:47] offset:29568
	s_waitcnt vmcnt(0)
	v_cmp_gt_u32_e32 vcc, 64, v9
	s_and_saveexec_b64 s[28:29], vcc
	ds_write_b128 v14, v[48:51] offset:33792
	s_mov_b64 exec, s[28:29]

; __device__ __forceinline__ int otid(int wvi) { int t = (wvi & 3) * 64 + lane_id(); asm volatile("" : "+v"(t)); return t; }
; __device__ __forceinline__ int srccol(int mode, int n) {
;     ...
;     const int tile = n >> 8, r = n & 255, bj = r >> 7, wc = (r >> 5) & 3, q = (r >> 4) & 1, i = r & 15;
;     return (q ? DFF : 0) + tile * 128 + wc * 32 + (i >> 2) * 8 + bj * 4 + (i & 3);
;   }
;   const int L = (n & ~31) + perm32(n & 31);
;   if (L < 2304) return L;
;   if (L < 3072) return L + 16;
;   if (L < 3088) return L - 768;
;   return -1;
; }
; __device__ __forceinline__ void prep_conv_item(const Params& p, int l, int it, char* smem, int wvi) {
;   const int tid = otid(wvi);
;   const float* src; bf16_t* dst; int ld, K, mode, KT;
;   if (it < 2816) { const int i = it / 1408; it -= i * 1408; src = p.ffn_w_in + (size_t)(l * 2 + i) * DM * 2 * DFF; dst = i ? p.wFin1 : p.wFin0; ld = 2 * DFF; K = DM; mode = 1; KT = 16; }
;   else if (it < 4224) { it -= 2816; const int i = it / 704; it -= i * 704; src = p.ffn_w_out + (size_t)(l * 2 + i) * DFF * DM; dst = i ? p.wFout1 : p.wFout0; ld = DM; K = DFF; mode = 0; KT = 44; }
;   else if (it < 5056) { it -= 4224; src = p.w_in + (size_t)l * DM * DIN; dst = p.wIn; ld = DIN; K = DM; mode = 2; KT = 16; }
;   else { it -= 5056; src = p.w_out + (size_t)l * DM * DM; dst = p.wOut; ld = DM; K = DM; mode = 0; KT = 16; }
;   const int ntile = it / KT, ktile = it - ntile * KT;
;   const int n0 = ntile * 64, k0 = ktile * 64;
;   float* sT = reinterpret_cast<float*>(smem);
;   __syncthreads();
; #pragma unroll 4
;   for (int i = 0; i < 16; ++i) {
;     const int idx = tid + 256 * i, k = idx >> 6, n = idx & 63;
;     const int sc = srccol(mode, n0 + n);
;     sT[k * 65 + n] = (sc >= 0) ? src[(size_t)(k0 + k) * ld + sc] : 0.f;
;   }
.LBB0_1051:
	s_mul_hi_i32 s2, s0, 0x2e8ba2e9
	s_lshr_b32 s3, s2, 31
	s_ashr_i32 s2, s2, 8
	s_add_i32 s2, s2, s3
	s_mul_i32 s3, s2, 0xfffffa80
	s_add_i32 s2, s1, s2
	v_readlane_b32 s8, v246, 6
	s_add_i32 s4, s3, s0
	s_mul_hi_i32 s3, s2, 0x1600000
	s_mul_i32 s2, s2, 0x1600000
	v_readlane_b32 s22, v246, 20
	v_readlane_b32 s23, v246, 21
	s_add_u32 s6, s22, s2
	s_addc_u32 s7, s23, s3
	s_cmpk_gt_i32 s0, 0xfa80
	s_movk_i32 s2, 0xf0
	s_cselect_b32 s2, s2, 0xf8
	s_add_u32 s2, s90, s2
	s_addc_u32 s3, s91, 0
	s_ashr_i32 s8, s4, 31
	s_lshr_b32 s8, s8, 28
	v_readlane_b32 s9, v246, 7
	s_add_i32 s8, s4, s8
	v_readlane_b32 s10, v246, 8
	s_ashr_i32 s9, s8, 4
	v_mbcnt_lo_u32_b32 v0, -1, 0
	v_mbcnt_hi_u32_b32 v0, -1, v0
	s_lshl_b32 s10, s9, 10
	v_add_u32_e32 v3, s95, v0
	s_lshl_b32 s4, s4, 6
	s_load_dwordx2 s[2:3], s[2:3], 0x0
	s_lshl_b32 s8, s9, 6
	s_sub_i32 s4, s4, s10
	v_bfe_i32 v1, v3, 4, 1
	s_lshl_b32 s10, s9, 5
	v_lshlrev_b32_e32 v4, 1, v3
	s_lshl_b32 s9, s9, 1
	v_and_b32_e32 v2, 63, v3
	v_and_b32_e32 v1, 0xb00, v1
	s_and_b32 s10, s10, 0xffffff80
	v_and_b32_e32 v4, 24, v4
	s_and_b32 s9, s9, 4
	v_and_b32_e32 v5, 3, v3
	v_bitop3_b32 v0, s8, v208, v2 bitop3:0xc8
	v_add_u32_e32 v1, s10, v1
	v_or3_b32 v4, v4, v5, s9
	v_or3_b32 v176, v4, v0, v1
	s_mov_b32 s5, 0
	v_cmp_lt_i32_e32 vcc, -1, v1
	v_lshl_add_u64 v[0:1], v[176:177], 2, s[6:7]
	v_lshl_add_u32 v2, v2, 2, s52
	v_readlane_b32 s11, v246, 9
	v_readlane_b32 s12, v246, 10
	v_readlane_b32 s13, v246, 11
	v_readlane_b32 s14, v246, 12
	v_readlane_b32 s15, v246, 13
	v_readlane_b32 s16, v246, 14
	v_readlane_b32 s17, v246, 15
	v_readlane_b32 s18, v246, 16
	v_readlane_b32 s19, v246, 17
	v_readlane_b32 s20, v246, 18
	v_readlane_b32 s21, v246, 19
	s_waitcnt lgkmcnt(0)
	s_barrier
	v_ashrrev_i32_e32 v30, 6, v3
	v_add_u32_e32 v31, s4, v30
	v_mad_i64_i32 v[26:27], s[10:11], v31, s66, v[0:1]
	v_mad_u64_u32 v[28:29], s[10:11], v30, s56, v[2:3]
	v_mov_b32_e32 v10, 0
	v_mov_b32_e32 v11, 0
	v_mov_b32_e32 v12, 0
	v_mov_b32_e32 v13, 0
	v_mov_b32_e32 v14, 0
	v_mov_b32_e32 v15, 0
	v_mov_b32_e32 v16, 0
	v_mov_b32_e32 v17, 0
	v_mov_b32_e32 v18, 0
	v_mov_b32_e32 v19, 0
	v_mov_b32_e32 v20, 0
	v_mov_b32_e32 v21, 0
	v_mov_b32_e32 v22, 0
	v_mov_b32_e32 v23, 0
	v_mov_b32_e32 v24, 0
	v_mov_b32_e32 v25, 0
	s_lshl_b32 s10, s66, 2
	s_mov_b32 s11, 0
	s_and_saveexec_b64 s[6:7], vcc
	global_load_dword v10, v[26:27], off
	v_lshl_add_u64 v[26:27], v[26:27], 0, s[10:11]
	global_load_dword v11, v[26:27], off
	v_lshl_add_u64 v[26:27], v[26:27], 0, s[10:11]
	global_load_dword v12, v[26:27], off
	v_lshl_add_u64 v[26:27], v[26:27], 0, s[10:11]
	global_load_dword v13, v[26:27], off
	v_lshl_add_u64 v[26:27], v[26:27], 0, s[10:11]
	global_load_dword v14, v[26:27], off
	v_lshl_add_u64 v[26:27], v[26:27], 0, s[10:11]
	global_load_dword v15, v[26:27], off
	v_lshl_add_u64 v[26:27], v[26:27], 0, s[10:11]
	global_load_dword v16, v[26:27], off
	v_lshl_add_u64 v[26:27], v[26:27], 0, s[10:11]
	global_load_dword v17, v[26:27], off
	v_lshl_add_u64 v[26:27], v[26:27], 0, s[10:11]
	global_load_dword v18, v[26:27], off
	v_lshl_add_u64 v[26:27], v[26:27], 0, s[10:11]
	global_load_dword v19, v[26:27], off
	v_lshl_add_u64 v[26:27], v[26:27], 0, s[10:11]
	global_load_dword v20, v[26:27], off
	v_lshl_add_u64 v[26:27], v[26:27], 0, s[10:11]
	global_load_dword v21, v[26:27], off
	v_lshl_add_u64 v[26:27], v[26:27], 0, s[10:11]
	global_load_dword v22, v[26:27], off
	v_lshl_add_u64 v[26:27], v[26:27], 0, s[10:11]
	global_load_dword v23, v[26:27], off
	v_lshl_add_u64 v[26:27], v[26:27], 0, s[10:11]
	global_load_dword v24, v[26:27], off
	v_lshl_add_u64 v[26:27], v[26:27], 0, s[10:11]
	global_load_dword v25, v[26:27], off
	s_or_b64 exec, exec, s[6:7]
	s_waitcnt vmcnt(15)
	ds_write_b32 v28, v10
	s_waitcnt vmcnt(14)
	ds_write_b32 v28, v11 offset:1040
	s_waitcnt vmcnt(13)
	ds_write_b32 v28, v12 offset:2080
	s_waitcnt vmcnt(12)
	ds_write_b32 v28, v13 offset:3120
	s_waitcnt vmcnt(11)
	ds_write_b32 v28, v14 offset:4160
	s_waitcnt vmcnt(10)
	ds_write_b32 v28, v15 offset:5200
	s_waitcnt vmcnt(9)
	ds_write_b32 v28, v16 offset:6240
	s_waitcnt vmcnt(8)
	ds_write_b32 v28, v17 offset:7280
	s_waitcnt vmcnt(7)
	ds_write_b32 v28, v18 offset:8320
	s_waitcnt vmcnt(6)
	ds_write_b32 v28, v19 offset:9360
	s_waitcnt vmcnt(5)
	ds_write_b32 v28, v20 offset:10400
	s_waitcnt vmcnt(4)
	ds_write_b32 v28, v21 offset:11440
	s_waitcnt vmcnt(3)
	ds_write_b32 v28, v22 offset:12480
	s_waitcnt vmcnt(2)
	ds_write_b32 v28, v23 offset:13520
	s_waitcnt vmcnt(1)
	ds_write_b32 v28, v24 offset:14560
	s_waitcnt vmcnt(0)
	ds_write_b32 v28, v25 offset:15600
	s_branch .LBB0_1050

; __device__ __forceinline__ int srccol(int mode, int n) {
;     ...
;   const int L = (n & ~31) + perm32(n & 31);
;   if (L < 2304) return L;
;   if (L < 3072) return L + 16;
;   if (L < 3088) return L - 768;
;   return -1;
; }
; __device__ __forceinline__ void prep_conv_item(const Params& p, int l, int it, char* smem, int wvi) {
;     ...
;   const int ntile = it / KT, ktile = it - ntile * KT;
;   const int n0 = ntile * 64, k0 = ktile * 64;
;   float* sT = reinterpret_cast<float*>(smem);
;   __syncthreads();
.LBB0_1129:
	v_cvt_f32_u32_e32 v0, s15
	s_add_u32 s2, s90, s2
	s_addc_u32 s3, s91, s3
	s_sub_i32 s13, 0, s15
	v_rcp_iflag_f32_e32 v0, v0
	s_abs_i32 s12, s1
	s_ashr_i32 s8, s1, 31
	v_bfe_i32 v3, v1, 4, 1
	v_mul_f32_e32 v0, 0x4f7ffffe, v0
	v_cvt_u32_f32_e32 v0, v0
	v_and_b32_e32 v3, 0xb00, v3
	v_lshlrev_b32_e32 v4, 1, v1
	v_and_b32_e32 v4, 24, v4
	v_readfirstlane_b32 s16, v0
	s_mul_i32 s13, s13, s16
	s_mul_hi_u32 s13, s16, s13
	s_add_i32 s16, s16, s13
	s_mul_hi_u32 s13, s12, s16
	s_mul_i32 s16, s13, s15
	s_sub_i32 s12, s12, s16
	s_add_i32 s17, s13, 1
	s_sub_i32 s16, s12, s15
	s_cmp_ge_u32 s12, s15
	s_cselect_b32 s13, s17, s13
	s_cselect_b32 s12, s16, s12
	s_add_i32 s16, s13, 1
	s_cmp_ge_u32 s12, s15
	s_cselect_b32 s12, s16, s13
	s_xor_b32 s12, s12, s8
	s_sub_i32 s12, s12, s8
	s_mul_i32 s8, s12, s15
	s_lshl_b32 s13, s12, 5
	s_sub_i32 s8, s1, s8
	s_lshl_b32 s1, s12, 6
	v_and_b32_e32 v0, 63, v1
	s_and_b32 s13, s13, 0xffffff80
	s_lshl_b32 s12, s12, 1
	v_bitop3_b32 v2, s1, v208, v0 bitop3:0xc8
	v_add_u32_e32 v3, s13, v3
	s_and_b32 s12, s12, 4
	v_or3_b32 v2, v3, v2, s12
	v_and_b32_e32 v3, 3, v1
	v_or3_b32 v2, v2, v3, v4
	v_lshrrev_b32_e32 v3, 2, v1
	v_and_b32_e32 v3, 4, v3
	v_bitop3_b32 v5, s1, v209, v0 bitop3:0xc8
	s_load_dwordx2 s[2:3], s[2:3], 0x0
	s_lshl_b32 s8, s8, 6
	v_or3_b32 v3, v3, v5, v4
	s_movk_i32 s12, 0xc10
	s_cmpk_lt_u32 s1, 0xc00
	v_add_u32_e32 v4, 0xfffffd00, v3
	v_cmp_gt_u32_e32 vcc, s12, v3
	v_add_u32_e32 v5, 16, v3
	s_movk_i32 s12, 0x900
	v_cndmask_b32_e32 v4, -1, v4, vcc
	s_cselect_b64 vcc, -1, 0
	v_cndmask_b32_e32 v4, v4, v5, vcc
	v_cmp_gt_i32_e32 vcc, s12, v3
	s_mov_b32 s14, 0
	v_lshl_add_u32 v0, v0, 2, s52
	v_cndmask_b32_e32 v4, v4, v3, vcc
	s_waitcnt lgkmcnt(0)
	s_barrier
	s_cmp_lt_i32 s9, 1
	v_mov_b32_e32 v176, v3
	s_cbranch_scc1 .LBB0_1136
	s_cmp_lg_u32 s9, 1
	s_mov_b64 s[12:13], -1
	s_cbranch_scc0 .LBB0_1134
	s_mov_b64 s[12:13], 0

; __device__ __forceinline__ void prep_conv_item(const Params& p, int l, int it, char* smem, int wvi) {
;     ...
; #pragma unroll 4
;   for (int i = 0; i < 16; ++i) {
;     const int idx = tid + 256 * i, k = idx >> 6, n = idx & 63;
;     const int sc = srccol(mode, n0 + n);
;     sT[k * 65 + n] = (sc >= 0) ? src[(size_t)(k0 + k) * ld + sc] : 0.f;
;   }
.LBB0_1136:
	v_ashrrev_i32_e32 v30, 6, v1
	v_add_u32_e32 v31, s8, v30
	v_ashrrev_i32_e32 v32, 31, v31
	v_mul_lo_u32 v33, s10, v32
	v_mul_lo_u32 v34, s11, v31
	v_mad_u64_u32 v[26:27], s[16:17], s10, v31, 0
	v_add3_u32 v27, v27, v33, v34
	v_lshl_add_u64 v[26:27], v[26:27], 2, s[6:7]
	v_lshl_add_u64 v[26:27], v[176:177], 2, v[26:27]
	v_mad_u64_u32 v[28:29], s[16:17], v30, s56, v[0:1]
	v_mov_b32_e32 v10, 0
	v_mov_b32_e32 v11, 0
	v_mov_b32_e32 v12, 0
	v_mov_b32_e32 v13, 0
	v_mov_b32_e32 v14, 0
	v_mov_b32_e32 v15, 0
	v_mov_b32_e32 v16, 0
	v_mov_b32_e32 v17, 0
	v_mov_b32_e32 v18, 0
	v_mov_b32_e32 v19, 0
	v_mov_b32_e32 v20, 0
	v_mov_b32_e32 v21, 0
	v_mov_b32_e32 v22, 0
	v_mov_b32_e32 v23, 0
	v_mov_b32_e32 v24, 0
	v_mov_b32_e32 v25, 0
	v_cmp_lt_i32_e32 vcc, -1, v176
	s_lshl_b64 s[16:17], s[10:11], 4
	s_and_saveexec_b64 s[12:13], vcc
	global_load_dword v10, v[26:27], off
	v_lshl_add_u64 v[26:27], v[26:27], 0, s[16:17]
	global_load_dword v11, v[26:27], off
	v_lshl_add_u64 v[26:27], v[26:27], 0, s[16:17]
	global_load_dword v12, v[26:27], off
	v_lshl_add_u64 v[26:27], v[26:27], 0, s[16:17]
	global_load_dword v13, v[26:27], off
	v_lshl_add_u64 v[26:27], v[26:27], 0, s[16:17]
	global_load_dword v14, v[26:27], off
	v_lshl_add_u64 v[26:27], v[26:27], 0, s[16:17]
	global_load_dword v15, v[26:27], off
	v_lshl_add_u64 v[26:27], v[26:27], 0, s[16:17]
	global_load_dword v16, v[26:27], off
	v_lshl_add_u64 v[26:27], v[26:27], 0, s[16:17]
	global_load_dword v17, v[26:27], off
	v_lshl_add_u64 v[26:27], v[26:27], 0, s[16:17]
	global_load_dword v18, v[26:27], off
	v_lshl_add_u64 v[26:27], v[26:27], 0, s[16:17]
	global_load_dword v19, v[26:27], off
	v_lshl_add_u64 v[26:27], v[26:27], 0, s[16:17]
	global_load_dword v20, v[26:27], off
	v_lshl_add_u64 v[26:27], v[26:27], 0, s[16:17]
	global_load_dword v21, v[26:27], off
	v_lshl_add_u64 v[26:27], v[26:27], 0, s[16:17]
	global_load_dword v22, v[26:27], off
	v_lshl_add_u64 v[26:27], v[26:27], 0, s[16:17]
	global_load_dword v23, v[26:27], off
	v_lshl_add_u64 v[26:27], v[26:27], 0, s[16:17]
	global_load_dword v24, v[26:27], off
	v_lshl_add_u64 v[26:27], v[26:27], 0, s[16:17]
	global_load_dword v25, v[26:27], off
	s_or_b64 exec, exec, s[12:13]
	s_waitcnt vmcnt(15)
	ds_write_b32 v28, v10
	s_waitcnt vmcnt(14)
	ds_write_b32 v28, v11 offset:1040
	s_waitcnt vmcnt(13)
	ds_write_b32 v28, v12 offset:2080
	s_waitcnt vmcnt(12)
	ds_write_b32 v28, v13 offset:3120
	s_waitcnt vmcnt(11)
	ds_write_b32 v28, v14 offset:4160
	s_waitcnt vmcnt(10)
	ds_write_b32 v28, v15 offset:5200
	s_waitcnt vmcnt(9)
	ds_write_b32 v28, v16 offset:6240
	s_waitcnt vmcnt(8)
	ds_write_b32 v28, v17 offset:7280
	s_waitcnt vmcnt(7)
	ds_write_b32 v28, v18 offset:8320
	s_waitcnt vmcnt(6)
	ds_write_b32 v28, v19 offset:9360
	s_waitcnt vmcnt(5)
	ds_write_b32 v28, v20 offset:10400
	s_waitcnt vmcnt(4)
	ds_write_b32 v28, v21 offset:11440
	s_waitcnt vmcnt(3)
	ds_write_b32 v28, v22 offset:12480
	s_waitcnt vmcnt(2)
	ds_write_b32 v28, v23 offset:13520
	s_waitcnt vmcnt(1)
	ds_write_b32 v28, v24 offset:14560
	s_waitcnt vmcnt(0)
	ds_write_b32 v28, v25 offset:15600
	s_branch .LBB0_1119

; __device__ __forceinline__ int otid(int wvi) { int t = (wvi & 3) * 64 + lane_id(); asm volatile("" : "+v"(t)); return t; }
; __device__ __forceinline__ int srccol(int mode, int n) {
;     ...
;     const int tile = n >> 8, r = n & 255, bj = r >> 7, wc = (r >> 5) & 3, q = (r >> 4) & 1, i = r & 15;
;     return (q ? DFF : 0) + tile * 128 + wc * 32 + (i >> 2) * 8 + bj * 4 + (i & 3);
;   }
;   const int L = (n & ~31) + perm32(n & 31);
;   if (L < 2304) return L;
;   if (L < 3072) return L + 16;
;   if (L < 3088) return L - 768;
;   return -1;
; }
; __device__ __forceinline__ void prep_conv_item(const Params& p, int l, int it, char* smem, int wvi) {
;   const int tid = otid(wvi);
;   const float* src; bf16_t* dst; int ld, K, mode, KT;
;   if (it < 2816) { const int i = it / 1408; it -= i * 1408; src = p.ffn_w_in + (size_t)(l * 2 + i) * DM * 2 * DFF; dst = i ? p.wFin1 : p.wFin0; ld = 2 * DFF; K = DM; mode = 1; KT = 16; }
;   else if (it < 4224) { it -= 2816; const int i = it / 704; it -= i * 704; src = p.ffn_w_out + (size_t)(l * 2 + i) * DFF * DM; dst = i ? p.wFout1 : p.wFout0; ld = DM; K = DFF; mode = 0; KT = 44; }
;   else if (it < 5056) { it -= 4224; src = p.w_in + (size_t)l * DM * DIN; dst = p.wIn; ld = DIN; K = DM; mode = 2; KT = 16; }
;   else { it -= 5056; src = p.w_out + (size_t)l * DM * DM; dst = p.wOut; ld = DM; K = DM; mode = 0; KT = 16; }
;   const int ntile = it / KT, ktile = it - ntile * KT;
;   const int n0 = ntile * 64, k0 = ktile * 64;
;   float* sT = reinterpret_cast<float*>(smem);
;   __syncthreads();
; #pragma unroll 4
;   for (int i = 0; i < 16; ++i) {
;     const int idx = tid + 256 * i, k = idx >> 6, n = idx & 63;
;     const int sc = srccol(mode, n0 + n);
;     sT[k * 65 + n] = (sc >= 0) ? src[(size_t)(k0 + k) * ld + sc] : 0.f;
;   }
.LBB0_1162:
	s_add_i32 s1, s0, 0x580
	s_mul_hi_i32 s2, s1, 0x2e8ba2e9
	s_lshr_b32 s3, s2, 31
	s_ashr_i32 s2, s2, 8
	s_add_i32 s2, s2, s3
	s_mul_i32 s3, s2, 0xfffffa80
	v_readlane_b32 s8, v246, 6
	s_add_i32 s4, s3, s1
	s_mul_hi_i32 s1, s2, 0x1600000
	s_mul_i32 s2, s2, 0x1600000
	v_readlane_b32 s22, v246, 20
	v_readlane_b32 s23, v246, 21
	s_add_u32 s6, s22, s2
	s_addc_u32 s7, s23, s1
	s_cmp_gt_u32 s0, 0xfffff500
	s_movk_i32 s1, 0xf0
	s_cselect_b32 s1, s1, 0xf8
	s_add_u32 s2, s90, s1
	s_addc_u32 s3, s91, 0
	s_ashr_i32 s1, s4, 31
	s_lshr_b32 s1, s1, 28
	s_add_i32 s1, s4, s1
	v_readlane_b32 s9, v246, 7
	s_ashr_i32 s8, s1, 4
	v_mbcnt_lo_u32_b32 v0, -1, 0
	v_mbcnt_hi_u32_b32 v0, -1, v0
	s_lshl_b32 s9, s8, 10
	v_add_u32_e32 v3, s95, v0
	s_lshl_b32 s4, s4, 6
	s_load_dwordx2 s[2:3], s[2:3], 0x0
	s_lshl_b32 s1, s8, 6
	s_sub_i32 s4, s4, s9
	v_bfe_i32 v1, v3, 4, 1
	s_lshl_b32 s9, s8, 5
	v_lshlrev_b32_e32 v4, 1, v3
	s_lshl_b32 s8, s8, 1
	v_and_b32_e32 v2, 63, v3
	v_and_b32_e32 v1, 0xb00, v1
	s_and_b32 s9, s9, 0xffffff80
	v_and_b32_e32 v4, 24, v4
	s_and_b32 s8, s8, 4
	v_and_b32_e32 v5, 3, v3
	v_bitop3_b32 v0, s1, v208, v2 bitop3:0xc8
	v_add_u32_e32 v1, s9, v1
	v_or3_b32 v4, v4, v5, s8
	v_or3_b32 v176, v4, v0, v1
	s_mov_b32 s5, 0
	v_cmp_lt_i32_e32 vcc, -1, v1
	v_lshl_add_u64 v[0:1], v[176:177], 2, s[6:7]
	v_lshl_add_u32 v2, v2, 2, s52
	v_readlane_b32 s10, v246, 8
	v_readlane_b32 s11, v246, 9
	v_readlane_b32 s12, v246, 10
	v_readlane_b32 s13, v246, 11
	v_readlane_b32 s14, v246, 12
	v_readlane_b32 s15, v246, 13
	v_readlane_b32 s16, v246, 14
	v_readlane_b32 s17, v246, 15
	v_readlane_b32 s18, v246, 16
	v_readlane_b32 s19, v246, 17
	v_readlane_b32 s20, v246, 18
	v_readlane_b32 s21, v246, 19
	s_waitcnt lgkmcnt(0)
	s_barrier
	v_ashrrev_i32_e32 v30, 6, v3
	v_add_u32_e32 v31, s4, v30
	v_mad_i64_i32 v[26:27], s[8:9], v31, s66, v[0:1]
	v_mad_u64_u32 v[28:29], s[8:9], v30, s56, v[2:3]
	v_mov_b32_e32 v10, 0
	v_mov_b32_e32 v11, 0
	v_mov_b32_e32 v12, 0
	v_mov_b32_e32 v13, 0
	v_mov_b32_e32 v14, 0
	v_mov_b32_e32 v15, 0
	v_mov_b32_e32 v16, 0
	v_mov_b32_e32 v17, 0
	v_mov_b32_e32 v18, 0
	v_mov_b32_e32 v19, 0
	v_mov_b32_e32 v20, 0
	v_mov_b32_e32 v21, 0
	v_mov_b32_e32 v22, 0
	v_mov_b32_e32 v23, 0
	v_mov_b32_e32 v24, 0
	v_mov_b32_e32 v25, 0
	s_lshl_b32 s8, s66, 2
	s_mov_b32 s9, 0
	s_and_saveexec_b64 s[6:7], vcc
	global_load_dword v10, v[26:27], off
	v_lshl_add_u64 v[26:27], v[26:27], 0, s[8:9]
	global_load_dword v11, v[26:27], off
	v_lshl_add_u64 v[26:27], v[26:27], 0, s[8:9]
	global_load_dword v12, v[26:27], off
	v_lshl_add_u64 v[26:27], v[26:27], 0, s[8:9]
	global_load_dword v13, v[26:27], off
	v_lshl_add_u64 v[26:27], v[26:27], 0, s[8:9]
	global_load_dword v14, v[26:27], off
	v_lshl_add_u64 v[26:27], v[26:27], 0, s[8:9]
	global_load_dword v15, v[26:27], off
	v_lshl_add_u64 v[26:27], v[26:27], 0, s[8:9]
	global_load_dword v16, v[26:27], off
	v_lshl_add_u64 v[26:27], v[26:27], 0, s[8:9]
	global_load_dword v17, v[26:27], off
	v_lshl_add_u64 v[26:27], v[26:27], 0, s[8:9]
	global_load_dword v18, v[26:27], off
	v_lshl_add_u64 v[26:27], v[26:27], 0, s[8:9]
	global_load_dword v19, v[26:27], off
	v_lshl_add_u64 v[26:27], v[26:27], 0, s[8:9]
	global_load_dword v20, v[26:27], off
	v_lshl_add_u64 v[26:27], v[26:27], 0, s[8:9]
	global_load_dword v21, v[26:27], off
	v_lshl_add_u64 v[26:27], v[26:27], 0, s[8:9]
	global_load_dword v22, v[26:27], off
	v_lshl_add_u64 v[26:27], v[26:27], 0, s[8:9]
	global_load_dword v23, v[26:27], off
	v_lshl_add_u64 v[26:27], v[26:27], 0, s[8:9]
	global_load_dword v24, v[26:27], off
	v_lshl_add_u64 v[26:27], v[26:27], 0, s[8:9]
	global_load_dword v25, v[26:27], off
	s_or_b64 exec, exec, s[6:7]
	s_waitcnt vmcnt(15)
	ds_write_b32 v28, v10
	s_waitcnt vmcnt(14)
	ds_write_b32 v28, v11 offset:1040
	s_waitcnt vmcnt(13)
	ds_write_b32 v28, v12 offset:2080
	s_waitcnt vmcnt(12)
	ds_write_b32 v28, v13 offset:3120
	s_waitcnt vmcnt(11)
	ds_write_b32 v28, v14 offset:4160
	s_waitcnt vmcnt(10)
	ds_write_b32 v28, v15 offset:5200
	s_waitcnt vmcnt(9)
	ds_write_b32 v28, v16 offset:6240
	s_waitcnt vmcnt(8)
	ds_write_b32 v28, v17 offset:7280
	s_waitcnt vmcnt(7)
	ds_write_b32 v28, v18 offset:8320
	s_waitcnt vmcnt(6)
	ds_write_b32 v28, v19 offset:9360
	s_waitcnt vmcnt(5)
	ds_write_b32 v28, v20 offset:10400
	s_waitcnt vmcnt(4)
	ds_write_b32 v28, v21 offset:11440
	s_waitcnt vmcnt(3)
	ds_write_b32 v28, v22 offset:12480
	s_waitcnt vmcnt(2)
	ds_write_b32 v28, v23 offset:13520
	s_waitcnt vmcnt(1)
	ds_write_b32 v28, v24 offset:14560
	s_waitcnt vmcnt(0)
	ds_write_b32 v28, v25 offset:15600
	s_branch .LBB0_1161

; __device__ __forceinline__ void prep_conv_item(const Params& p, int l, int it, char* smem, int wvi) {
;     ...
;   const int ntile = it / KT, ktile = it - ntile * KT;
;   const int n0 = ntile * 64, k0 = ktile * 64;
;   float* sT = reinterpret_cast<float*>(smem);
;   __syncthreads();
; #pragma unroll 4
;   for (int i = 0; i < 16; ++i) {
;     const int idx = tid + 256 * i, k = idx >> 6, n = idx & 63;
;     const int sc = srccol(mode, n0 + n);
;     sT[k * 65 + n] = (sc >= 0) ? src[(size_t)(k0 + k) * ld + sc] : 0.f;
;   }
.LBB0_1178:
	v_cvt_f32_ubyte0_e32 v0, s7
	v_rcp_iflag_f32_e32 v0, v0
	v_readlane_b32 s10, v245, 47
	s_add_u32 s8, s90, s8
	v_readlane_b32 s11, v245, 48
	v_mul_f32_e32 v0, 0x4f7ffffe, v0
	v_cvt_u32_f32_e32 v0, v0
	s_addc_u32 s9, s91, s11
	s_sub_i32 s14, 0, s7
	s_abs_i32 s11, s1
	v_readfirstlane_b32 s15, v0
	s_mul_i32 s14, s14, s15
	s_mul_hi_u32 s14, s15, s14
	s_add_i32 s15, s15, s14
	s_mul_hi_u32 s14, s11, s15
	s_mul_i32 s15, s14, s7
	s_sub_i32 s11, s11, s15
	s_ashr_i32 s10, s1, 31
	s_add_i32 s15, s14, 1
	s_sub_i32 s16, s11, s7
	s_cmp_ge_u32 s11, s7
	s_cselect_b32 s14, s15, s14
	s_cselect_b32 s11, s16, s11
	s_add_i32 s15, s14, 1
	s_cmp_ge_u32 s11, s7
	s_cselect_b32 s11, s15, s14
	s_xor_b32 s11, s11, s10
	s_sub_i32 s11, s11, s10
	s_mul_i32 s7, s11, s7
	s_sub_i32 s7, s1, s7
	s_lshl_b32 s10, s7, 6
	v_bfe_i32 v1, v3, 4, 1
	s_lshl_b32 s7, s11, 5
	s_lshl_b32 s1, s11, 6
	v_and_b32_e32 v2, 63, v3
	v_and_b32_e32 v1, 0xb00, v1
	s_and_b32 s7, s7, 0xffffff80
	v_or_b32_e32 v0, s1, v2
	v_add_u32_e32 v1, s7, v1
	s_movk_i32 s7, 0x60
	v_and_or_b32 v1, v0, s7, v1
	s_lshl_b32 s7, s11, 1
	s_and_b32 s7, s7, 4
	v_and_b32_e32 v5, 3, v3
	v_or3_b32 v1, v1, s7, v5
	v_lshrrev_b32_e32 v5, 2, v3
	s_load_dwordx2 s[8:9], s[8:9], 0x0
	v_and_b32_e32 v5, 4, v5
	s_movk_i32 s7, 0xffe3
	v_and_or_b32 v0, v0, s7, v5
	v_lshlrev_b32_e32 v4, 1, v3
	v_cndmask_b32_e64 v0, v1, v0, s[4:5]
	v_and_or_b32 v176, v4, 24, v0
	s_mov_b32 s3, 0
	v_cmp_lt_i32_e32 vcc, -1, v0
	v_lshl_add_u64 v[0:1], v[176:177], 2, s[12:13]
	v_lshl_add_u32 v2, v2, 2, s52
	s_waitcnt lgkmcnt(0)
	s_barrier
	v_ashrrev_i32_e32 v30, 6, v3
	v_add_u32_e32 v31, s10, v30
	v_mad_i64_i32 v[26:27], s[12:13], s6, v31, 0
	v_lshl_add_u64 v[26:27], v[26:27], 2, v[0:1]
	v_mad_u64_u32 v[28:29], s[12:13], v30, s56, v[2:3]
	v_mov_b32_e32 v10, 0
	v_mov_b32_e32 v11, 0
	v_mov_b32_e32 v12, 0
	v_mov_b32_e32 v13, 0
	v_mov_b32_e32 v14, 0
	v_mov_b32_e32 v15, 0
	v_mov_b32_e32 v16, 0
	v_mov_b32_e32 v17, 0
	v_mov_b32_e32 v18, 0
	v_mov_b32_e32 v19, 0
	v_mov_b32_e32 v20, 0
	v_mov_b32_e32 v21, 0
	v_mov_b32_e32 v22, 0
	v_mov_b32_e32 v23, 0
	v_mov_b32_e32 v24, 0
	v_mov_b32_e32 v25, 0
	s_lshl_b32 s12, s6, 4
	s_mov_b32 s13, 0
	s_and_saveexec_b64 s[4:5], vcc
	global_load_dword v10, v[26:27], off
	v_lshl_add_u64 v[26:27], v[26:27], 0, s[12:13]
	global_load_dword v11, v[26:27], off
	v_lshl_add_u64 v[26:27], v[26:27], 0, s[12:13]
	global_load_dword v12, v[26:27], off
	v_lshl_add_u64 v[26:27], v[26:27], 0, s[12:13]
	global_load_dword v13, v[26:27], off
	v_lshl_add_u64 v[26:27], v[26:27], 0, s[12:13]
	global_load_dword v14, v[26:27], off
	v_lshl_add_u64 v[26:27], v[26:27], 0, s[12:13]
	global_load_dword v15, v[26:27], off
	v_lshl_add_u64 v[26:27], v[26:27], 0, s[12:13]
	global_load_dword v16, v[26:27], off
	v_lshl_add_u64 v[26:27], v[26:27], 0, s[12:13]
	global_load_dword v17, v[26:27], off
	v_lshl_add_u64 v[26:27], v[26:27], 0, s[12:13]
	global_load_dword v18, v[26:27], off
	v_lshl_add_u64 v[26:27], v[26:27], 0, s[12:13]
	global_load_dword v19, v[26:27], off
	v_lshl_add_u64 v[26:27], v[26:27], 0, s[12:13]
	global_load_dword v20, v[26:27], off
	v_lshl_add_u64 v[26:27], v[26:27], 0, s[12:13]
	global_load_dword v21, v[26:27], off
	v_lshl_add_u64 v[26:27], v[26:27], 0, s[12:13]
	global_load_dword v22, v[26:27], off
	v_lshl_add_u64 v[26:27], v[26:27], 0, s[12:13]
	global_load_dword v23, v[26:27], off
	v_lshl_add_u64 v[26:27], v[26:27], 0, s[12:13]
	global_load_dword v24, v[26:27], off
	v_lshl_add_u64 v[26:27], v[26:27], 0, s[12:13]
	global_load_dword v25, v[26:27], off
	s_or_b64 exec, exec, s[4:5]
	s_waitcnt vmcnt(15)
	ds_write_b32 v28, v10
	s_waitcnt vmcnt(14)
	ds_write_b32 v28, v11 offset:1040
	s_waitcnt vmcnt(13)
	ds_write_b32 v28, v12 offset:2080
	s_waitcnt vmcnt(12)
	ds_write_b32 v28, v13 offset:3120
	s_waitcnt vmcnt(11)
	ds_write_b32 v28, v14 offset:4160
	s_waitcnt vmcnt(10)
	ds_write_b32 v28, v15 offset:5200
	s_waitcnt vmcnt(9)
	ds_write_b32 v28, v16 offset:6240
	s_waitcnt vmcnt(8)
	ds_write_b32 v28, v17 offset:7280
	s_waitcnt vmcnt(7)
	ds_write_b32 v28, v18 offset:8320
	s_waitcnt vmcnt(6)
	ds_write_b32 v28, v19 offset:9360
	s_waitcnt vmcnt(5)
	ds_write_b32 v28, v20 offset:10400
	s_waitcnt vmcnt(4)
	ds_write_b32 v28, v21 offset:11440
	s_waitcnt vmcnt(3)
	ds_write_b32 v28, v22 offset:12480
	s_waitcnt vmcnt(2)
	ds_write_b32 v28, v23 offset:13520
	s_waitcnt vmcnt(1)
	ds_write_b32 v28, v24 offset:14560
	s_waitcnt vmcnt(0)
	ds_write_b32 v28, v25 offset:15600
	s_branch .LBB0_1172

; __device__ __forceinline__ int otid(int wvi) { int t = (wvi & 3) * 64 + lane_id(); asm volatile("" : "+v"(t)); return t; }
; __device__ __forceinline__ int srccol(int mode, int n) {
;     ...
;     const int tile = n >> 8, r = n & 255, bj = r >> 7, wc = (r >> 5) & 3, q = (r >> 4) & 1, i = r & 15;
;     return (q ? DFF : 0) + tile * 128 + wc * 32 + (i >> 2) * 8 + bj * 4 + (i & 3);
;   }
;   const int L = (n & ~31) + perm32(n & 31);
;   if (L < 2304) return L;
;   if (L < 3072) return L + 16;
;   if (L < 3088) return L - 768;
;   return -1;
; }
; __device__ __forceinline__ void prep_conv_item(const Params& p, int l, int it, char* smem, int wvi) {
;   const int tid = otid(wvi);
;   const float* src; bf16_t* dst; int ld, K, mode, KT;
;   if (it < 2816) { const int i = it / 1408; it -= i * 1408; src = p.ffn_w_in + (size_t)(l * 2 + i) * DM * 2 * DFF; dst = i ? p.wFin1 : p.wFin0; ld = 2 * DFF; K = DM; mode = 1; KT = 16; }
;   else if (it < 4224) { it -= 2816; const int i = it / 704; it -= i * 704; src = p.ffn_w_out + (size_t)(l * 2 + i) * DFF * DM; dst = i ? p.wFout1 : p.wFout0; ld = DM; K = DFF; mode = 0; KT = 44; }
;   else if (it < 5056) { it -= 4224; src = p.w_in + (size_t)l * DM * DIN; dst = p.wIn; ld = DIN; K = DM; mode = 2; KT = 16; }
;   else { it -= 5056; src = p.w_out + (size_t)l * DM * DM; dst = p.wOut; ld = DM; K = DM; mode = 0; KT = 16; }
;   const int ntile = it / KT, ktile = it - ntile * KT;
;   const int n0 = ntile * 64, k0 = ktile * 64;
;   float* sT = reinterpret_cast<float*>(smem);
;   __syncthreads();
; #pragma unroll 4
;   for (int i = 0; i < 16; ++i) {
;     const int idx = tid + 256 * i, k = idx >> 6, n = idx & 63;
;     const int sc = srccol(mode, n0 + n);
;     sT[k * 65 + n] = (sc >= 0) ? src[(size_t)(k0 + k) * ld + sc] : 0.f;
;   }
.LBB0_1292:
	s_mul_hi_i32 s1, s0, 0x2e8ba2e9
	s_lshr_b32 s2, s1, 31
	s_ashr_i32 s1, s1, 8
	s_add_i32 s1, s1, s2
	s_mul_i32 s2, s1, 0xfffffa80
	v_readlane_b32 s8, v246, 6
	s_add_i32 s4, s2, s0
	s_mul_hi_i32 s2, s1, 0x1600000
	s_mul_i32 s1, s1, 0x1600000
	v_readlane_b32 s22, v246, 20
	v_readlane_b32 s23, v246, 21
	s_add_u32 s6, s22, s1
	s_addc_u32 s7, s23, s2
	s_cmpk_gt_i32 s0, 0xfa80
	s_movk_i32 s1, 0xf0
	s_cselect_b32 s1, s1, 0xf8
	s_add_u32 s2, s90, s1
	s_addc_u32 s3, s91, 0
	s_ashr_i32 s1, s4, 31
	s_lshr_b32 s1, s1, 28
	s_add_i32 s1, s4, s1
	v_readlane_b32 s9, v246, 7
	s_ashr_i32 s8, s1, 4
	s_waitcnt vmcnt(1)
	v_mbcnt_lo_u32_b32 v0, -1, 0
	v_mbcnt_hi_u32_b32 v0, -1, v0
	s_lshl_b32 s9, s8, 10
	v_add_u32_e32 v3, s95, v0
	s_lshl_b32 s4, s4, 6
	s_load_dwordx2 s[2:3], s[2:3], 0x0
	s_lshl_b32 s1, s8, 6
	s_sub_i32 s4, s4, s9
	v_bfe_i32 v1, v3, 4, 1
	s_lshl_b32 s9, s8, 5
	s_waitcnt vmcnt(0)
	v_lshlrev_b32_e32 v4, 1, v3
	s_lshl_b32 s8, s8, 1
	v_and_b32_e32 v2, 63, v3
	v_and_b32_e32 v1, 0xb00, v1
	s_and_b32 s9, s9, 0xffffff80
	v_and_b32_e32 v4, 24, v4
	s_and_b32 s8, s8, 4
	v_and_b32_e32 v5, 3, v3
	v_bitop3_b32 v0, s1, v208, v2 bitop3:0xc8
	v_add_u32_e32 v1, s9, v1
	v_or3_b32 v4, v4, v5, s8
	v_or3_b32 v176, v4, v0, v1
	s_mov_b32 s5, 0
	v_cmp_lt_i32_e32 vcc, -1, v1
	v_lshl_add_u64 v[0:1], v[176:177], 2, s[6:7]
	v_lshl_add_u32 v2, v2, 2, s52
	v_readlane_b32 s10, v246, 8
	v_readlane_b32 s11, v246, 9
	v_readlane_b32 s12, v246, 10
	v_readlane_b32 s13, v246, 11
	v_readlane_b32 s14, v246, 12
	v_readlane_b32 s15, v246, 13
	v_readlane_b32 s16, v246, 14
	v_readlane_b32 s17, v246, 15
	v_readlane_b32 s18, v246, 16
	v_readlane_b32 s19, v246, 17
	v_readlane_b32 s20, v246, 18
	v_readlane_b32 s21, v246, 19
	s_waitcnt lgkmcnt(0)
	s_barrier
	v_ashrrev_i32_e32 v30, 6, v3
	v_add_u32_e32 v31, s4, v30
	v_mad_i64_i32 v[26:27], s[8:9], v31, s66, v[0:1]
	v_mad_u64_u32 v[28:29], s[8:9], v30, s56, v[2:3]
	v_mov_b32_e32 v10, 0
	v_mov_b32_e32 v11, 0
	v_mov_b32_e32 v12, 0
	v_mov_b32_e32 v13, 0
	v_mov_b32_e32 v14, 0
	v_mov_b32_e32 v15, 0
	v_mov_b32_e32 v16, 0
	v_mov_b32_e32 v17, 0
	v_mov_b32_e32 v18, 0
	v_mov_b32_e32 v19, 0
	v_mov_b32_e32 v20, 0
	v_mov_b32_e32 v21, 0
	v_mov_b32_e32 v22, 0
	v_mov_b32_e32 v23, 0
	v_mov_b32_e32 v24, 0
	v_mov_b32_e32 v25, 0
	s_lshl_b32 s8, s66, 2
	s_mov_b32 s9, 0
	s_and_saveexec_b64 s[6:7], vcc
	global_load_dword v10, v[26:27], off
	v_lshl_add_u64 v[26:27], v[26:27], 0, s[8:9]
	global_load_dword v11, v[26:27], off
	v_lshl_add_u64 v[26:27], v[26:27], 0, s[8:9]
	global_load_dword v12, v[26:27], off
	v_lshl_add_u64 v[26:27], v[26:27], 0, s[8:9]
	global_load_dword v13, v[26:27], off
	v_lshl_add_u64 v[26:27], v[26:27], 0, s[8:9]
	global_load_dword v14, v[26:27], off
	v_lshl_add_u64 v[26:27], v[26:27], 0, s[8:9]
	global_load_dword v15, v[26:27], off
	v_lshl_add_u64 v[26:27], v[26:27], 0, s[8:9]
	global_load_dword v16, v[26:27], off
	v_lshl_add_u64 v[26:27], v[26:27], 0, s[8:9]
	global_load_dword v17, v[26:27], off
	v_lshl_add_u64 v[26:27], v[26:27], 0, s[8:9]
	global_load_dword v18, v[26:27], off
	v_lshl_add_u64 v[26:27], v[26:27], 0, s[8:9]
	global_load_dword v19, v[26:27], off
	v_lshl_add_u64 v[26:27], v[26:27], 0, s[8:9]
	global_load_dword v20, v[26:27], off
	v_lshl_add_u64 v[26:27], v[26:27], 0, s[8:9]
	global_load_dword v21, v[26:27], off
	v_lshl_add_u64 v[26:27], v[26:27], 0, s[8:9]
	global_load_dword v22, v[26:27], off
	v_lshl_add_u64 v[26:27], v[26:27], 0, s[8:9]
	global_load_dword v23, v[26:27], off
	v_lshl_add_u64 v[26:27], v[26:27], 0, s[8:9]
	global_load_dword v24, v[26:27], off
	v_lshl_add_u64 v[26:27], v[26:27], 0, s[8:9]
	global_load_dword v25, v[26:27], off
	s_or_b64 exec, exec, s[6:7]
	s_waitcnt vmcnt(15)
	ds_write_b32 v28, v10
	s_waitcnt vmcnt(14)
	ds_write_b32 v28, v11 offset:1040
	s_waitcnt vmcnt(13)
	ds_write_b32 v28, v12 offset:2080
	s_waitcnt vmcnt(12)
	ds_write_b32 v28, v13 offset:3120
	s_waitcnt vmcnt(11)
	ds_write_b32 v28, v14 offset:4160
	s_waitcnt vmcnt(10)
	ds_write_b32 v28, v15 offset:5200
	s_waitcnt vmcnt(9)
	ds_write_b32 v28, v16 offset:6240
	s_waitcnt vmcnt(8)
	ds_write_b32 v28, v17 offset:7280
	s_waitcnt vmcnt(7)
	ds_write_b32 v28, v18 offset:8320
	s_waitcnt vmcnt(6)
	ds_write_b32 v28, v19 offset:9360
	s_waitcnt vmcnt(5)
	ds_write_b32 v28, v20 offset:10400
	s_waitcnt vmcnt(4)
	ds_write_b32 v28, v21 offset:11440
	s_waitcnt vmcnt(3)
	ds_write_b32 v28, v22 offset:12480
	s_waitcnt vmcnt(2)
	ds_write_b32 v28, v23 offset:13520
	s_waitcnt vmcnt(1)
	ds_write_b32 v28, v24 offset:14560
	s_waitcnt vmcnt(0)
	ds_write_b32 v28, v25 offset:15600
	s_branch .LBB0_1291

; __device__ __forceinline__ void prep_conv_item(const Params& p, int l, int it, char* smem, int wvi) {
;     ...
;   const int ntile = it / KT, ktile = it - ntile * KT;
;   const int n0 = ntile * 64, k0 = ktile * 64;
;   float* sT = reinterpret_cast<float*>(smem);
;   __syncthreads();
; #pragma unroll 4
;   for (int i = 0; i < 16; ++i) {
;     const int idx = tid + 256 * i, k = idx >> 6, n = idx & 63;
;     const int sc = srccol(mode, n0 + n);
;     sT[k * 65 + n] = (sc >= 0) ? src[(size_t)(k0 + k) * ld + sc] : 0.f;
;   }
.LBB0_1314:
	v_cvt_f32_ubyte0_e32 v0, s3
	v_rcp_iflag_f32_e32 v0, v0
	s_add_u32 s8, s90, s8
	s_addc_u32 s9, s91, s9
	s_sub_i32 s15, 0, s3
	v_mul_f32_e32 v0, 0x4f7ffffe, v0
	v_cvt_u32_f32_e32 v0, v0
	s_abs_i32 s14, s10
	s_ashr_i32 s11, s10, 31
	v_bfe_i32 v1, v3, 4, 1
	v_readfirstlane_b32 s16, v0
	s_mul_i32 s15, s15, s16
	s_mul_hi_u32 s15, s16, s15
	s_add_i32 s16, s16, s15
	s_mul_hi_u32 s15, s14, s16
	s_mul_i32 s16, s15, s3
	s_sub_i32 s14, s14, s16
	s_add_i32 s16, s15, 1
	s_sub_i32 s17, s14, s3
	s_cmp_ge_u32 s14, s3
	s_cselect_b32 s15, s16, s15
	s_cselect_b32 s14, s17, s14
	s_add_i32 s16, s15, 1
	s_cmp_ge_u32 s14, s3
	s_cselect_b32 s14, s16, s15
	s_xor_b32 s14, s14, s11
	s_sub_i32 s11, s14, s11
	s_mul_i32 s3, s11, s3
	s_lshl_b32 s14, s11, 5
	s_sub_i32 s10, s10, s3
	s_lshl_b32 s3, s11, 6
	v_and_b32_e32 v2, 63, v3
	v_and_b32_e32 v1, 0xb00, v1
	s_and_b32 s14, s14, 0xffffff80
	v_or_b32_e32 v0, s3, v2
	v_add_u32_e32 v1, s14, v1
	s_movk_i32 s14, 0x60
	s_lshl_b32 s11, s11, 1
	v_and_or_b32 v1, v0, s14, v1
	s_and_b32 s11, s11, 4
	v_and_b32_e32 v5, 3, v3
	v_or3_b32 v1, v1, s11, v5
	v_lshrrev_b32_e32 v5, 2, v3
	s_load_dwordx2 s[8:9], s[8:9], 0x0
	v_and_b32_e32 v5, 4, v5
	s_movk_i32 s11, 0xffe3
	v_and_or_b32 v0, v0, s11, v5
	v_lshlrev_b32_e32 v4, 1, v3
	v_cndmask_b32_e64 v0, v1, v0, s[4:5]
	v_and_or_b32 v176, v4, 24, v0
	s_mov_b32 s7, 0
	s_lshl_b32 s10, s10, 6
	v_cmp_lt_i32_e32 vcc, -1, v0
	v_lshl_add_u64 v[0:1], v[176:177], 2, s[12:13]
	v_lshl_add_u32 v2, v2, 2, s52
	s_waitcnt lgkmcnt(0)
	s_barrier
	v_ashrrev_i32_e32 v30, 6, v3
	v_add_u32_e32 v31, s10, v30
	v_mad_i64_i32 v[26:27], s[12:13], s6, v31, 0
	v_lshl_add_u64 v[26:27], v[26:27], 2, v[0:1]
	v_mad_u64_u32 v[28:29], s[12:13], v30, s56, v[2:3]
	v_mov_b32_e32 v10, 0
	v_mov_b32_e32 v11, 0
	v_mov_b32_e32 v12, 0
	v_mov_b32_e32 v13, 0
	v_mov_b32_e32 v14, 0
	v_mov_b32_e32 v15, 0
	v_mov_b32_e32 v16, 0
	v_mov_b32_e32 v17, 0
	v_mov_b32_e32 v18, 0
	v_mov_b32_e32 v19, 0
	v_mov_b32_e32 v20, 0
	v_mov_b32_e32 v21, 0
	v_mov_b32_e32 v22, 0
	v_mov_b32_e32 v23, 0
	v_mov_b32_e32 v24, 0
	v_mov_b32_e32 v25, 0
	s_lshl_b32 s12, s6, 4
	s_mov_b32 s13, 0
	s_and_saveexec_b64 s[4:5], vcc
	global_load_dword v10, v[26:27], off
	v_lshl_add_u64 v[26:27], v[26:27], 0, s[12:13]
	global_load_dword v11, v[26:27], off
	v_lshl_add_u64 v[26:27], v[26:27], 0, s[12:13]
	global_load_dword v12, v[26:27], off
	v_lshl_add_u64 v[26:27], v[26:27], 0, s[12:13]
	global_load_dword v13, v[26:27], off
	v_lshl_add_u64 v[26:27], v[26:27], 0, s[12:13]
	global_load_dword v14, v[26:27], off
	v_lshl_add_u64 v[26:27], v[26:27], 0, s[12:13]
	global_load_dword v15, v[26:27], off
	v_lshl_add_u64 v[26:27], v[26:27], 0, s[12:13]
	global_load_dword v16, v[26:27], off
	v_lshl_add_u64 v[26:27], v[26:27], 0, s[12:13]
	global_load_dword v17, v[26:27], off
	v_lshl_add_u64 v[26:27], v[26:27], 0, s[12:13]
	global_load_dword v18, v[26:27], off
	v_lshl_add_u64 v[26:27], v[26:27], 0, s[12:13]
	global_load_dword v19, v[26:27], off
	v_lshl_add_u64 v[26:27], v[26:27], 0, s[12:13]
	global_load_dword v20, v[26:27], off
	v_lshl_add_u64 v[26:27], v[26:27], 0, s[12:13]
	global_load_dword v21, v[26:27], off
	v_lshl_add_u64 v[26:27], v[26:27], 0, s[12:13]
	global_load_dword v22, v[26:27], off
	v_lshl_add_u64 v[26:27], v[26:27], 0, s[12:13]
	global_load_dword v23, v[26:27], off
	v_lshl_add_u64 v[26:27], v[26:27], 0, s[12:13]
	global_load_dword v24, v[26:27], off
	v_lshl_add_u64 v[26:27], v[26:27], 0, s[12:13]
	global_load_dword v25, v[26:27], off
	s_or_b64 exec, exec, s[4:5]
	s_waitcnt vmcnt(15)
	ds_write_b32 v28, v10
	s_waitcnt vmcnt(14)
	ds_write_b32 v28, v11 offset:1040
	s_waitcnt vmcnt(13)
	ds_write_b32 v28, v12 offset:2080
	s_waitcnt vmcnt(12)
	ds_write_b32 v28, v13 offset:3120
	s_waitcnt vmcnt(11)
	ds_write_b32 v28, v14 offset:4160
	s_waitcnt vmcnt(10)
	ds_write_b32 v28, v15 offset:5200
	s_waitcnt vmcnt(9)
	ds_write_b32 v28, v16 offset:6240
	s_waitcnt vmcnt(8)
	ds_write_b32 v28, v17 offset:7280
	s_waitcnt vmcnt(7)
	ds_write_b32 v28, v18 offset:8320
	s_waitcnt vmcnt(6)
	ds_write_b32 v28, v19 offset:9360
	s_waitcnt vmcnt(5)
	ds_write_b32 v28, v20 offset:10400
	s_waitcnt vmcnt(4)
	ds_write_b32 v28, v21 offset:11440
	s_waitcnt vmcnt(3)
	ds_write_b32 v28, v22 offset:12480
	s_waitcnt vmcnt(2)
	ds_write_b32 v28, v23 offset:13520
	s_waitcnt vmcnt(1)
	ds_write_b32 v28, v24 offset:14560
	s_waitcnt vmcnt(0)
	ds_write_b32 v28, v25 offset:15600
	s_branch .LBB0_1310
